# strategy: instruction selection - conv FMAs as two single f32 FMAs instead of one packed v_pk_fma_f32 (v28 otherwise)
# baseline (speedup 1.0000x reference)
; __device__ __forceinline__ f32x2v bf2(unsigned v) { return (f32x2v){bflo(v), bfhi(v)}; }
; __device__ __forceinline__ void mixer_prompt_run(const Args& p, int run, int c2) {
;     ...
;             for (int i = 0; i < 38; ++i) {
;                 const int ti = t0 + 8 * hh - 30 + i; unsigned v = U32[(rowb + (ti >= 0 ? ti : 0)) * 256 + c2]; v = (ti >= 0) ? v : 0u; const f32x2v x = bf2(v);
; #pragma unroll
;                 for (int t = 0; t < 8; ++t) { const int j = i - t; if (j >= 0 && j <= 30) a[t] = w[j] * x + a[t]; }
.Lmx_b0:
	v_lshlrev_b32_e32 v96, 16, v193
	v_and_b32_e32 v97, 0xffff0000, v193
	v_fma_f32 v172, v106, v96, v90
	v_fma_f32 v173, v107, v97, v91
	s_cbranch_vccnz .Lmx_e1
.Lmx_b1:
	v_lshlrev_b32_e32 v98, 16, v194
	v_and_b32_e32 v99, 0xffff0000, v194
	v_fmac_f32_e32 v172, v108, v98
	v_fmac_f32_e32 v173, v109, v99
	v_fma_f32 v174, v106, v98, v90
	v_fma_f32 v175, v107, v99, v91
	s_cbranch_vccnz .Lmx_e2
.Lmx_b2:
	v_lshlrev_b32_e32 v96, 16, v195
	v_and_b32_e32 v97, 0xffff0000, v195
	v_fmac_f32_e32 v172, v110, v96
	v_fmac_f32_e32 v173, v111, v97
	v_fmac_f32_e32 v174, v108, v96
	v_fmac_f32_e32 v175, v109, v97
	v_fma_f32 v176, v106, v96, v90
	v_fma_f32 v177, v107, v97, v91
	s_cbranch_vccnz .Lmx_e3
.Lmx_b3:
	v_lshlrev_b32_e32 v98, 16, v196
	v_and_b32_e32 v99, 0xffff0000, v196
	v_fmac_f32_e32 v172, v112, v98
	v_fmac_f32_e32 v173, v113, v99
	v_fmac_f32_e32 v174, v110, v98
	v_fmac_f32_e32 v175, v111, v99
	v_fmac_f32_e32 v176, v108, v98
	v_fmac_f32_e32 v177, v109, v99
	v_fma_f32 v178, v106, v98, v90
	v_fma_f32 v179, v107, v99, v91
	s_cbranch_vccnz .Lmx_e4
.Lmx_b4:
	v_lshlrev_b32_e32 v96, 16, v197
	v_and_b32_e32 v97, 0xffff0000, v197
	v_fmac_f32_e32 v172, v114, v96
	v_fmac_f32_e32 v173, v115, v97
	v_fmac_f32_e32 v174, v112, v96
	v_fmac_f32_e32 v175, v113, v97
	v_fmac_f32_e32 v176, v110, v96
	v_fmac_f32_e32 v177, v111, v97
	v_fmac_f32_e32 v178, v108, v96
	v_fmac_f32_e32 v179, v109, v97
	v_fma_f32 v180, v106, v96, v90
	v_fma_f32 v181, v107, v97, v91
	s_cbranch_vccnz .Lmx_e5
.Lmx_b5:
	v_lshlrev_b32_e32 v98, 16, v198
	v_and_b32_e32 v99, 0xffff0000, v198
	v_fmac_f32_e32 v172, v116, v98
	v_fmac_f32_e32 v173, v117, v99
	v_fmac_f32_e32 v174, v114, v98
	v_fmac_f32_e32 v175, v115, v99
	v_fmac_f32_e32 v176, v112, v98
	v_fmac_f32_e32 v177, v113, v99
	v_fmac_f32_e32 v178, v110, v98
	v_fmac_f32_e32 v179, v111, v99
	v_fmac_f32_e32 v180, v108, v98
	v_fmac_f32_e32 v181, v109, v99
	v_fma_f32 v182, v106, v98, v90
	v_fma_f32 v183, v107, v99, v91
	s_cbranch_vccnz .Lmx_e6
.Lmx_b6:
	v_lshlrev_b32_e32 v96, 16, v199
	v_and_b32_e32 v97, 0xffff0000, v199
	v_fmac_f32_e32 v172, v118, v96
	v_fmac_f32_e32 v173, v119, v97
	v_fmac_f32_e32 v174, v116, v96
	v_fmac_f32_e32 v175, v117, v97
	v_fmac_f32_e32 v176, v114, v96
	v_fmac_f32_e32 v177, v115, v97
	v_fmac_f32_e32 v178, v112, v96
	v_fmac_f32_e32 v179, v113, v97
	v_fmac_f32_e32 v180, v110, v96
	v_fmac_f32_e32 v181, v111, v97
	v_fmac_f32_e32 v182, v108, v96
	v_fmac_f32_e32 v183, v109, v97
	v_fma_f32 v184, v106, v96, v90
	v_fma_f32 v185, v107, v97, v91
	s_cbranch_vccnz .Lmx_e7
.Lmx_b7:
	v_lshlrev_b32_e32 v98, 16, v200
	v_and_b32_e32 v99, 0xffff0000, v200
	v_fmac_f32_e32 v172, v120, v98
	v_fmac_f32_e32 v173, v121, v99
	v_fmac_f32_e32 v174, v118, v98
	v_fmac_f32_e32 v175, v119, v99
	v_fmac_f32_e32 v176, v116, v98
	v_fmac_f32_e32 v177, v117, v99
	v_fmac_f32_e32 v178, v114, v98
	v_fmac_f32_e32 v179, v115, v99
	v_fmac_f32_e32 v180, v112, v98
	v_fmac_f32_e32 v181, v113, v99
	v_fmac_f32_e32 v182, v110, v98
	v_fmac_f32_e32 v183, v111, v99
	v_fmac_f32_e32 v184, v108, v98
	v_fmac_f32_e32 v185, v109, v99
	v_fma_f32 v186, v106, v98, v90
	v_fma_f32 v187, v107, v99, v91
	s_cbranch_vccnz .Lmx_e8
.Lmx_b8:
	v_lshlrev_b32_e32 v96, 16, v201
	v_and_b32_e32 v97, 0xffff0000, v201
	v_fmac_f32_e32 v172, v122, v96
	v_fmac_f32_e32 v173, v123, v97
	v_fmac_f32_e32 v174, v120, v96
	v_fmac_f32_e32 v175, v121, v97
	v_fmac_f32_e32 v176, v118, v96
	v_fmac_f32_e32 v177, v119, v97
	v_fmac_f32_e32 v178, v116, v96
	v_fmac_f32_e32 v179, v117, v97
	v_fmac_f32_e32 v180, v114, v96
	v_fmac_f32_e32 v181, v115, v97
	v_fmac_f32_e32 v182, v112, v96
	v_fmac_f32_e32 v183, v113, v97
	v_fmac_f32_e32 v184, v110, v96
	v_fmac_f32_e32 v185, v111, v97
	v_fmac_f32_e32 v186, v108, v96
	v_fmac_f32_e32 v187, v109, v97
	v_fma_f32 v188, v106, v96, v90
	v_fma_f32 v189, v107, v97, v91
	s_cbranch_vccnz .Lmx_e9
.Lmx_b9:
	v_lshlrev_b32_e32 v98, 16, v202
	v_and_b32_e32 v99, 0xffff0000, v202
	v_fmac_f32_e32 v172, v124, v98
	v_fmac_f32_e32 v173, v125, v99
	v_fmac_f32_e32 v174, v122, v98
	v_fmac_f32_e32 v175, v123, v99
	v_fmac_f32_e32 v176, v120, v98
	v_fmac_f32_e32 v177, v121, v99
	v_fmac_f32_e32 v178, v118, v98
	v_fmac_f32_e32 v179, v119, v99
	v_fmac_f32_e32 v180, v116, v98
	v_fmac_f32_e32 v181, v117, v99
	v_fmac_f32_e32 v182, v114, v98
	v_fmac_f32_e32 v183, v115, v99
	v_fmac_f32_e32 v184, v112, v98
	v_fmac_f32_e32 v185, v113, v99
	v_fmac_f32_e32 v186, v110, v98
	v_fmac_f32_e32 v187, v111, v99
	v_fmac_f32_e32 v188, v108, v98
	v_fmac_f32_e32 v189, v109, v99
	v_fma_f32 v190, v106, v98, v90
	v_fma_f32 v191, v107, v99, v91
	s_cbranch_vccnz .Lmx_e10
.Lmx_b10:
	v_lshlrev_b32_e32 v96, 16, v203
	v_and_b32_e32 v97, 0xffff0000, v203
	v_fmac_f32_e32 v172, v126, v96
	v_fmac_f32_e32 v173, v127, v97
	v_fmac_f32_e32 v174, v124, v96
	v_fmac_f32_e32 v175, v125, v97
	v_fmac_f32_e32 v176, v122, v96
	v_fmac_f32_e32 v177, v123, v97
	v_fmac_f32_e32 v178, v120, v96
	v_fmac_f32_e32 v179, v121, v97
	v_fmac_f32_e32 v180, v118, v96
	v_fmac_f32_e32 v181, v119, v97
	v_fmac_f32_e32 v182, v116, v96
	v_fmac_f32_e32 v183, v117, v97
	v_fmac_f32_e32 v184, v114, v96
	v_fmac_f32_e32 v185, v115, v97
	v_fmac_f32_e32 v186, v112, v96
	v_fmac_f32_e32 v187, v113, v97
	v_fmac_f32_e32 v188, v110, v96
	v_fmac_f32_e32 v189, v111, v97
	v_fmac_f32_e32 v190, v108, v96
	v_fmac_f32_e32 v191, v109, v97
	v_fma_f32 v78, v106, v96, v90
	v_fma_f32 v79, v107, v97, v91
	s_cbranch_vccnz .Lmx_e11
; __device__ __forceinline__ f32x2v bf2(unsigned v) { return (f32x2v){bflo(v), bfhi(v)}; }
; __device__ __forceinline__ void mixer_prompt_run(const Args& p, int run, int c2) {
;     ...
;             for (int i = 0; i < 38; ++i) {
;                 const int ti = t0 + 8 * hh - 30 + i; unsigned v = U32[(rowb + (ti >= 0 ? ti : 0)) * 256 + c2]; v = (ti >= 0) ? v : 0u; const f32x2v x = bf2(v);
; #pragma unroll
;                 for (int t = 0; t < 8; ++t) { const int j = i - t; if (j >= 0 && j <= 30) a[t] = w[j] * x + a[t]; }
;                 if (i == 18) asm volatile("" ::: "memory");
.Lmx_b11:
	v_lshlrev_b32_e32 v98, 16, v204
	v_and_b32_e32 v99, 0xffff0000, v204
	v_fmac_f32_e32 v172, v128, v98
	v_fmac_f32_e32 v173, v129, v99
	v_fmac_f32_e32 v174, v126, v98
	v_fmac_f32_e32 v175, v127, v99
	v_fmac_f32_e32 v176, v124, v98
	v_fmac_f32_e32 v177, v125, v99
	v_fmac_f32_e32 v178, v122, v98
	v_fmac_f32_e32 v179, v123, v99
	v_fmac_f32_e32 v180, v120, v98
	v_fmac_f32_e32 v181, v121, v99
	v_fmac_f32_e32 v182, v118, v98
	v_fmac_f32_e32 v183, v119, v99
	v_fmac_f32_e32 v184, v116, v98
	v_fmac_f32_e32 v185, v117, v99
	v_fmac_f32_e32 v186, v114, v98
	v_fmac_f32_e32 v187, v115, v99
	v_fmac_f32_e32 v188, v112, v98
	v_fmac_f32_e32 v189, v113, v99
	v_fmac_f32_e32 v190, v110, v98
	v_fmac_f32_e32 v191, v111, v99
	v_fmac_f32_e32 v78, v108, v98
	v_fmac_f32_e32 v79, v109, v99
	v_fma_f32 v80, v106, v98, v90
	v_fma_f32 v81, v107, v99, v91
	s_cbranch_vccnz .Lmx_e12
.Lmx_b12:
	v_lshlrev_b32_e32 v96, 16, v205
	v_and_b32_e32 v97, 0xffff0000, v205
	v_fmac_f32_e32 v172, v130, v96
	v_fmac_f32_e32 v173, v131, v97
	v_fmac_f32_e32 v174, v128, v96
	v_fmac_f32_e32 v175, v129, v97
	v_fmac_f32_e32 v176, v126, v96
	v_fmac_f32_e32 v177, v127, v97
	v_fmac_f32_e32 v178, v124, v96
	v_fmac_f32_e32 v179, v125, v97
	v_fmac_f32_e32 v180, v122, v96
	v_fmac_f32_e32 v181, v123, v97
	v_fmac_f32_e32 v182, v120, v96
	v_fmac_f32_e32 v183, v121, v97
	v_fmac_f32_e32 v184, v118, v96
	v_fmac_f32_e32 v185, v119, v97
	v_fmac_f32_e32 v186, v116, v96
	v_fmac_f32_e32 v187, v117, v97
	v_fmac_f32_e32 v188, v114, v96
	v_fmac_f32_e32 v189, v115, v97
	v_fmac_f32_e32 v190, v112, v96
	v_fmac_f32_e32 v191, v113, v97
	v_fmac_f32_e32 v78, v110, v96
	v_fmac_f32_e32 v79, v111, v97
	v_fmac_f32_e32 v80, v108, v96
	v_fmac_f32_e32 v81, v109, v97
	v_fma_f32 v82, v106, v96, v90
	v_fma_f32 v83, v107, v97, v91
	s_cbranch_vccnz .Lmx_e13
.Lmx_b13:
	v_lshlrev_b32_e32 v98, 16, v206
	v_and_b32_e32 v99, 0xffff0000, v206
	v_fmac_f32_e32 v172, v132, v98
	v_fmac_f32_e32 v173, v133, v99
	v_fmac_f32_e32 v174, v130, v98
	v_fmac_f32_e32 v175, v131, v99
	v_fmac_f32_e32 v176, v128, v98
	v_fmac_f32_e32 v177, v129, v99
	v_fmac_f32_e32 v178, v126, v98
	v_fmac_f32_e32 v179, v127, v99
	v_fmac_f32_e32 v180, v124, v98
	v_fmac_f32_e32 v181, v125, v99
	v_fmac_f32_e32 v182, v122, v98
	v_fmac_f32_e32 v183, v123, v99
	v_fmac_f32_e32 v184, v120, v98
	v_fmac_f32_e32 v185, v121, v99
	v_fmac_f32_e32 v186, v118, v98
	v_fmac_f32_e32 v187, v119, v99
	v_fmac_f32_e32 v188, v116, v98
	v_fmac_f32_e32 v189, v117, v99
	v_fmac_f32_e32 v190, v114, v98
	v_fmac_f32_e32 v191, v115, v99
	v_fmac_f32_e32 v78, v112, v98
	v_fmac_f32_e32 v79, v113, v99
	v_fmac_f32_e32 v80, v110, v98
	v_fmac_f32_e32 v81, v111, v99
	v_fmac_f32_e32 v82, v108, v98
	v_fmac_f32_e32 v83, v109, v99
	v_fma_f32 v84, v106, v98, v90
	v_fma_f32 v85, v107, v99, v91
	s_cbranch_vccnz .Lmx_e14
.Lmx_b14:
	v_lshlrev_b32_e32 v96, 16, v207
	v_and_b32_e32 v97, 0xffff0000, v207
	v_fmac_f32_e32 v172, v134, v96
	v_fmac_f32_e32 v173, v135, v97
	v_fmac_f32_e32 v174, v132, v96
	v_fmac_f32_e32 v175, v133, v97
	v_fmac_f32_e32 v176, v130, v96
	v_fmac_f32_e32 v177, v131, v97
	v_fmac_f32_e32 v178, v128, v96
	v_fmac_f32_e32 v179, v129, v97
	v_fmac_f32_e32 v180, v126, v96
	v_fmac_f32_e32 v181, v127, v97
	v_fmac_f32_e32 v182, v124, v96
	v_fmac_f32_e32 v183, v125, v97
	v_fmac_f32_e32 v184, v122, v96
	v_fmac_f32_e32 v185, v123, v97
	v_fmac_f32_e32 v186, v120, v96
	v_fmac_f32_e32 v187, v121, v97
	v_fmac_f32_e32 v188, v118, v96
	v_fmac_f32_e32 v189, v119, v97
	v_fmac_f32_e32 v190, v116, v96
	v_fmac_f32_e32 v191, v117, v97
	v_fmac_f32_e32 v78, v114, v96
	v_fmac_f32_e32 v79, v115, v97
	v_fmac_f32_e32 v80, v112, v96
	v_fmac_f32_e32 v81, v113, v97
	v_fmac_f32_e32 v82, v110, v96
	v_fmac_f32_e32 v83, v111, v97
	v_fmac_f32_e32 v84, v108, v96
	v_fmac_f32_e32 v85, v109, v97
	v_fma_f32 v86, v106, v96, v90
	v_fma_f32 v87, v107, v97, v91
	s_waitcnt vmcnt(30)
	s_cbranch_vccnz .Lmx_e15
.Lmx_b15:
	v_lshlrev_b32_e32 v98, 16, v208
	v_and_b32_e32 v99, 0xffff0000, v208
	v_fmac_f32_e32 v172, v136, v98
	v_fmac_f32_e32 v173, v137, v99
	v_fmac_f32_e32 v174, v134, v98
	v_fmac_f32_e32 v175, v135, v99
	v_fmac_f32_e32 v176, v132, v98
	v_fmac_f32_e32 v177, v133, v99
	v_fmac_f32_e32 v178, v130, v98
	v_fmac_f32_e32 v179, v131, v99
	v_fmac_f32_e32 v180, v128, v98
	v_fmac_f32_e32 v181, v129, v99
	v_fmac_f32_e32 v182, v126, v98
	v_fmac_f32_e32 v183, v127, v99
	v_fmac_f32_e32 v184, v124, v98
	v_fmac_f32_e32 v185, v125, v99
	v_fmac_f32_e32 v186, v122, v98
	v_fmac_f32_e32 v187, v123, v99
	v_fmac_f32_e32 v188, v120, v98
	v_fmac_f32_e32 v189, v121, v99
	v_fmac_f32_e32 v190, v118, v98
	v_fmac_f32_e32 v191, v119, v99
	v_fmac_f32_e32 v78, v116, v98
	v_fmac_f32_e32 v79, v117, v99
	v_fmac_f32_e32 v80, v114, v98
	v_fmac_f32_e32 v81, v115, v99
	v_fmac_f32_e32 v82, v112, v98
	v_fmac_f32_e32 v83, v113, v99
	v_fmac_f32_e32 v84, v110, v98
	v_fmac_f32_e32 v85, v111, v99
	v_fmac_f32_e32 v86, v108, v98
	v_fmac_f32_e32 v87, v109, v99
	v_fma_f32 v88, v106, v98, v90
	v_fma_f32 v89, v107, v99, v91
	s_waitcnt vmcnt(29)
	s_cbranch_vccnz .Lmx_e16
.Lmx_b16:
	v_lshlrev_b32_e32 v96, 16, v209
	v_and_b32_e32 v97, 0xffff0000, v209
	v_fmac_f32_e32 v172, v138, v96
	v_fmac_f32_e32 v173, v139, v97
	v_fmac_f32_e32 v174, v136, v96
	v_fmac_f32_e32 v175, v137, v97
	v_fmac_f32_e32 v176, v134, v96
	v_fmac_f32_e32 v177, v135, v97
	v_fmac_f32_e32 v178, v132, v96
	v_fmac_f32_e32 v179, v133, v97
	v_fmac_f32_e32 v180, v130, v96
	v_fmac_f32_e32 v181, v131, v97
	v_fmac_f32_e32 v182, v128, v96
	v_fmac_f32_e32 v183, v129, v97
	v_fmac_f32_e32 v184, v126, v96
	v_fmac_f32_e32 v185, v127, v97
	v_fmac_f32_e32 v186, v124, v96
	v_fmac_f32_e32 v187, v125, v97
	v_fmac_f32_e32 v188, v122, v96
	v_fmac_f32_e32 v189, v123, v97
	v_fmac_f32_e32 v190, v120, v96
	v_fmac_f32_e32 v191, v121, v97
	v_fmac_f32_e32 v78, v118, v96
	v_fmac_f32_e32 v79, v119, v97
	v_fmac_f32_e32 v80, v116, v96
	v_fmac_f32_e32 v81, v117, v97
	v_fmac_f32_e32 v82, v114, v96
	v_fmac_f32_e32 v83, v115, v97
	v_fmac_f32_e32 v84, v112, v96
	v_fmac_f32_e32 v85, v113, v97
	v_fmac_f32_e32 v86, v110, v96
	v_fmac_f32_e32 v87, v111, v97
	v_fmac_f32_e32 v88, v108, v96
	v_fmac_f32_e32 v89, v109, v97
	s_waitcnt vmcnt(28)
	s_cbranch_vccnz .Lmx_e17
; __device__ __forceinline__ f32x2v bf2(unsigned v) { return (f32x2v){bflo(v), bfhi(v)}; }
; __device__ __forceinline__ void mixer_prompt_run(const Args& p, int run, int c2) {
;     ...
;             for (int i = 0; i < 38; ++i) {
;                 const int ti = t0 + 8 * hh - 30 + i; unsigned v = U32[(rowb + (ti >= 0 ? ti : 0)) * 256 + c2]; v = (ti >= 0) ? v : 0u; const f32x2v x = bf2(v);
; #pragma unroll
;                 for (int t = 0; t < 8; ++t) { const int j = i - t; if (j >= 0 && j <= 30) a[t] = w[j] * x + a[t]; }
;                 if (i == 18) asm volatile("" ::: "memory");
.Lmx_b17:
	v_lshlrev_b32_e32 v98, 16, v210
	v_and_b32_e32 v99, 0xffff0000, v210
	v_fmac_f32_e32 v172, v140, v98
	v_fmac_f32_e32 v173, v141, v99
	v_fmac_f32_e32 v174, v138, v98
	v_fmac_f32_e32 v175, v139, v99
	v_fmac_f32_e32 v176, v136, v98
	v_fmac_f32_e32 v177, v137, v99
	v_fmac_f32_e32 v178, v134, v98
	v_fmac_f32_e32 v179, v135, v99
	v_fmac_f32_e32 v180, v132, v98
	v_fmac_f32_e32 v181, v133, v99
	v_fmac_f32_e32 v182, v130, v98
	v_fmac_f32_e32 v183, v131, v99
	v_fmac_f32_e32 v184, v128, v98
	v_fmac_f32_e32 v185, v129, v99
	v_fmac_f32_e32 v186, v126, v98
	v_fmac_f32_e32 v187, v127, v99
	v_fmac_f32_e32 v188, v124, v98
	v_fmac_f32_e32 v189, v125, v99
	v_fmac_f32_e32 v190, v122, v98
	v_fmac_f32_e32 v191, v123, v99
	v_fmac_f32_e32 v78, v120, v98
	v_fmac_f32_e32 v79, v121, v99
	v_fmac_f32_e32 v80, v118, v98
	v_fmac_f32_e32 v81, v119, v99
	v_fmac_f32_e32 v82, v116, v98
	v_fmac_f32_e32 v83, v117, v99
	v_fmac_f32_e32 v84, v114, v98
	v_fmac_f32_e32 v85, v115, v99
	v_fmac_f32_e32 v86, v112, v98
	v_fmac_f32_e32 v87, v113, v99
	v_fmac_f32_e32 v88, v110, v98
	v_fmac_f32_e32 v89, v111, v99
	s_waitcnt vmcnt(27)
	s_cbranch_vccnz .Lmx_e18
.Lmx_b18:
	v_lshlrev_b32_e32 v96, 16, v211
	v_and_b32_e32 v97, 0xffff0000, v211
	v_fmac_f32_e32 v172, v142, v96
	v_fmac_f32_e32 v173, v143, v97
	v_fmac_f32_e32 v174, v140, v96
	v_fmac_f32_e32 v175, v141, v97
	v_fmac_f32_e32 v176, v138, v96
	v_fmac_f32_e32 v177, v139, v97
	v_fmac_f32_e32 v178, v136, v96
	v_fmac_f32_e32 v179, v137, v97
	v_fmac_f32_e32 v180, v134, v96
	v_fmac_f32_e32 v181, v135, v97
	v_fmac_f32_e32 v182, v132, v96
	v_fmac_f32_e32 v183, v133, v97
	v_fmac_f32_e32 v184, v130, v96
	v_fmac_f32_e32 v185, v131, v97
	v_fmac_f32_e32 v186, v128, v96
	v_fmac_f32_e32 v187, v129, v97
	v_fmac_f32_e32 v188, v126, v96
	v_fmac_f32_e32 v189, v127, v97
	v_fmac_f32_e32 v190, v124, v96
	v_fmac_f32_e32 v191, v125, v97
	v_fmac_f32_e32 v78, v122, v96
	v_fmac_f32_e32 v79, v123, v97
	v_fmac_f32_e32 v80, v120, v96
	v_fmac_f32_e32 v81, v121, v97
	v_fmac_f32_e32 v82, v118, v96
	v_fmac_f32_e32 v83, v119, v97
	v_fmac_f32_e32 v84, v116, v96
	v_fmac_f32_e32 v85, v117, v97
	v_fmac_f32_e32 v86, v114, v96
	v_fmac_f32_e32 v87, v115, v97
	v_fmac_f32_e32 v88, v112, v96
	v_fmac_f32_e32 v89, v113, v97
	s_waitcnt vmcnt(26)
	s_cbranch_vccnz .Lmx_e19
.Lmx_b19:
	v_lshlrev_b32_e32 v98, 16, v212
	v_and_b32_e32 v99, 0xffff0000, v212
	v_fmac_f32_e32 v172, v144, v98
	v_fmac_f32_e32 v173, v145, v99
	v_fmac_f32_e32 v174, v142, v98
	v_fmac_f32_e32 v175, v143, v99
	v_fmac_f32_e32 v176, v140, v98
	v_fmac_f32_e32 v177, v141, v99
	v_fmac_f32_e32 v178, v138, v98
	v_fmac_f32_e32 v179, v139, v99
	v_fmac_f32_e32 v180, v136, v98
	v_fmac_f32_e32 v181, v137, v99
	v_fmac_f32_e32 v182, v134, v98
	v_fmac_f32_e32 v183, v135, v99
	v_fmac_f32_e32 v184, v132, v98
	v_fmac_f32_e32 v185, v133, v99
	v_fmac_f32_e32 v186, v130, v98
	v_fmac_f32_e32 v187, v131, v99
	v_fmac_f32_e32 v188, v128, v98
	v_fmac_f32_e32 v189, v129, v99
	v_fmac_f32_e32 v190, v126, v98
	v_fmac_f32_e32 v191, v127, v99
	v_fmac_f32_e32 v78, v124, v98
	v_fmac_f32_e32 v79, v125, v99
	v_fmac_f32_e32 v80, v122, v98
	v_fmac_f32_e32 v81, v123, v99
	v_fmac_f32_e32 v82, v120, v98
	v_fmac_f32_e32 v83, v121, v99
	v_fmac_f32_e32 v84, v118, v98
	v_fmac_f32_e32 v85, v119, v99
	v_fmac_f32_e32 v86, v116, v98
	v_fmac_f32_e32 v87, v117, v99
	v_fmac_f32_e32 v88, v114, v98
	v_fmac_f32_e32 v89, v115, v99
	s_waitcnt vmcnt(25)
	s_cbranch_vccnz .Lmx_e20
.Lmx_b20:
	v_lshlrev_b32_e32 v96, 16, v213
	v_and_b32_e32 v97, 0xffff0000, v213
	v_fmac_f32_e32 v172, v146, v96
	v_fmac_f32_e32 v173, v147, v97
	v_fmac_f32_e32 v174, v144, v96
	v_fmac_f32_e32 v175, v145, v97
	v_fmac_f32_e32 v176, v142, v96
	v_fmac_f32_e32 v177, v143, v97
	v_fmac_f32_e32 v178, v140, v96
	v_fmac_f32_e32 v179, v141, v97
	v_fmac_f32_e32 v180, v138, v96
	v_fmac_f32_e32 v181, v139, v97
	v_fmac_f32_e32 v182, v136, v96
	v_fmac_f32_e32 v183, v137, v97
	v_fmac_f32_e32 v184, v134, v96
	v_fmac_f32_e32 v185, v135, v97
	v_fmac_f32_e32 v186, v132, v96
	v_fmac_f32_e32 v187, v133, v97
	v_fmac_f32_e32 v188, v130, v96
	v_fmac_f32_e32 v189, v131, v97
	v_fmac_f32_e32 v190, v128, v96
	v_fmac_f32_e32 v191, v129, v97
	v_fmac_f32_e32 v78, v126, v96
	v_fmac_f32_e32 v79, v127, v97
	v_fmac_f32_e32 v80, v124, v96
	v_fmac_f32_e32 v81, v125, v97
	v_fmac_f32_e32 v82, v122, v96
	v_fmac_f32_e32 v83, v123, v97
	v_fmac_f32_e32 v84, v120, v96
	v_fmac_f32_e32 v85, v121, v97
	v_fmac_f32_e32 v86, v118, v96
	v_fmac_f32_e32 v87, v119, v97
	v_fmac_f32_e32 v88, v116, v96
	v_fmac_f32_e32 v89, v117, v97
	s_waitcnt vmcnt(24)
	s_cbranch_vccnz .Lmx_e21
.Lmx_b21:
	v_lshlrev_b32_e32 v98, 16, v214
	v_and_b32_e32 v99, 0xffff0000, v214
	v_fmac_f32_e32 v172, v148, v98
	v_fmac_f32_e32 v173, v149, v99
	v_fmac_f32_e32 v174, v146, v98
	v_fmac_f32_e32 v175, v147, v99
	v_fmac_f32_e32 v176, v144, v98
	v_fmac_f32_e32 v177, v145, v99
	v_fmac_f32_e32 v178, v142, v98
	v_fmac_f32_e32 v179, v143, v99
	v_fmac_f32_e32 v180, v140, v98
	v_fmac_f32_e32 v181, v141, v99
	v_fmac_f32_e32 v182, v138, v98
	v_fmac_f32_e32 v183, v139, v99
	v_fmac_f32_e32 v184, v136, v98
	v_fmac_f32_e32 v185, v137, v99
	v_fmac_f32_e32 v186, v134, v98
	v_fmac_f32_e32 v187, v135, v99
	v_fmac_f32_e32 v188, v132, v98
	v_fmac_f32_e32 v189, v133, v99
	v_fmac_f32_e32 v190, v130, v98
	v_fmac_f32_e32 v191, v131, v99
	v_fmac_f32_e32 v78, v128, v98
	v_fmac_f32_e32 v79, v129, v99
	v_fmac_f32_e32 v80, v126, v98
	v_fmac_f32_e32 v81, v127, v99
	v_fmac_f32_e32 v82, v124, v98
	v_fmac_f32_e32 v83, v125, v99
	v_fmac_f32_e32 v84, v122, v98
	v_fmac_f32_e32 v85, v123, v99
	v_fmac_f32_e32 v86, v120, v98
	v_fmac_f32_e32 v87, v121, v99
	v_fmac_f32_e32 v88, v118, v98
	v_fmac_f32_e32 v89, v119, v99
	s_waitcnt vmcnt(23)
	s_cbranch_vccnz .Lmx_e22
; __device__ __forceinline__ f32x2v bf2(unsigned v) { return (f32x2v){bflo(v), bfhi(v)}; }
; __device__ __forceinline__ void mixer_prompt_run(const Args& p, int run, int c2) {
;     ...
;             for (int i = 0; i < 38; ++i) {
;                 const int ti = t0 + 8 * hh - 30 + i; unsigned v = U32[(rowb + (ti >= 0 ? ti : 0)) * 256 + c2]; v = (ti >= 0) ? v : 0u; const f32x2v x = bf2(v);
; #pragma unroll
;                 for (int t = 0; t < 8; ++t) { const int j = i - t; if (j >= 0 && j <= 30) a[t] = w[j] * x + a[t]; }
;                 if (i == 18) asm volatile("" ::: "memory");
.Lmx_b22:
	v_lshlrev_b32_e32 v96, 16, v215
	v_and_b32_e32 v97, 0xffff0000, v215
	v_fmac_f32_e32 v172, v150, v96
	v_fmac_f32_e32 v173, v151, v97
	v_fmac_f32_e32 v174, v148, v96
	v_fmac_f32_e32 v175, v149, v97
	v_fmac_f32_e32 v176, v146, v96
	v_fmac_f32_e32 v177, v147, v97
	v_fmac_f32_e32 v178, v144, v96
	v_fmac_f32_e32 v179, v145, v97
	v_fmac_f32_e32 v180, v142, v96
	v_fmac_f32_e32 v181, v143, v97
	v_fmac_f32_e32 v182, v140, v96
	v_fmac_f32_e32 v183, v141, v97
	v_fmac_f32_e32 v184, v138, v96
	v_fmac_f32_e32 v185, v139, v97
	v_fmac_f32_e32 v186, v136, v96
	v_fmac_f32_e32 v187, v137, v97
	v_fmac_f32_e32 v188, v134, v96
	v_fmac_f32_e32 v189, v135, v97
	v_fmac_f32_e32 v190, v132, v96
	v_fmac_f32_e32 v191, v133, v97
	v_fmac_f32_e32 v78, v130, v96
	v_fmac_f32_e32 v79, v131, v97
	v_fmac_f32_e32 v80, v128, v96
	v_fmac_f32_e32 v81, v129, v97
	v_fmac_f32_e32 v82, v126, v96
	v_fmac_f32_e32 v83, v127, v97
	v_fmac_f32_e32 v84, v124, v96
	v_fmac_f32_e32 v85, v125, v97
	v_fmac_f32_e32 v86, v122, v96
	v_fmac_f32_e32 v87, v123, v97
	v_fmac_f32_e32 v88, v120, v96
	v_fmac_f32_e32 v89, v121, v97
	s_waitcnt vmcnt(22)
	s_cbranch_vccnz .Lmx_e23
.Lmx_b23:
	v_lshlrev_b32_e32 v98, 16, v216
	v_and_b32_e32 v99, 0xffff0000, v216
	v_fmac_f32_e32 v172, v152, v98
	v_fmac_f32_e32 v173, v153, v99
	v_fmac_f32_e32 v174, v150, v98
	v_fmac_f32_e32 v175, v151, v99
	v_fmac_f32_e32 v176, v148, v98
	v_fmac_f32_e32 v177, v149, v99
	v_fmac_f32_e32 v178, v146, v98
	v_fmac_f32_e32 v179, v147, v99
	v_fmac_f32_e32 v180, v144, v98
	v_fmac_f32_e32 v181, v145, v99
	v_fmac_f32_e32 v182, v142, v98
	v_fmac_f32_e32 v183, v143, v99
	v_fmac_f32_e32 v184, v140, v98
	v_fmac_f32_e32 v185, v141, v99
	v_fmac_f32_e32 v186, v138, v98
	v_fmac_f32_e32 v187, v139, v99
	v_fmac_f32_e32 v188, v136, v98
	v_fmac_f32_e32 v189, v137, v99
	v_fmac_f32_e32 v190, v134, v98
	v_fmac_f32_e32 v191, v135, v99
	v_fmac_f32_e32 v78, v132, v98
	v_fmac_f32_e32 v79, v133, v99
	v_fmac_f32_e32 v80, v130, v98
	v_fmac_f32_e32 v81, v131, v99
	v_fmac_f32_e32 v82, v128, v98
	v_fmac_f32_e32 v83, v129, v99
	v_fmac_f32_e32 v84, v126, v98
	v_fmac_f32_e32 v85, v127, v99
	v_fmac_f32_e32 v86, v124, v98
	v_fmac_f32_e32 v87, v125, v99
	v_fmac_f32_e32 v88, v122, v98
	v_fmac_f32_e32 v89, v123, v99
	s_waitcnt vmcnt(21)
	s_cbranch_vccnz .Lmx_e24
.Lmx_b24:
	v_lshlrev_b32_e32 v96, 16, v217
	v_and_b32_e32 v97, 0xffff0000, v217
	v_fmac_f32_e32 v172, v154, v96
	v_fmac_f32_e32 v173, v155, v97
	v_fmac_f32_e32 v174, v152, v96
	v_fmac_f32_e32 v175, v153, v97
	v_fmac_f32_e32 v176, v150, v96
	v_fmac_f32_e32 v177, v151, v97
	v_fmac_f32_e32 v178, v148, v96
	v_fmac_f32_e32 v179, v149, v97
	v_fmac_f32_e32 v180, v146, v96
	v_fmac_f32_e32 v181, v147, v97
	v_fmac_f32_e32 v182, v144, v96
	v_fmac_f32_e32 v183, v145, v97
	v_fmac_f32_e32 v184, v142, v96
	v_fmac_f32_e32 v185, v143, v97
	v_fmac_f32_e32 v186, v140, v96
	v_fmac_f32_e32 v187, v141, v97
	v_fmac_f32_e32 v188, v138, v96
	v_fmac_f32_e32 v189, v139, v97
	v_fmac_f32_e32 v190, v136, v96
	v_fmac_f32_e32 v191, v137, v97
	v_fmac_f32_e32 v78, v134, v96
	v_fmac_f32_e32 v79, v135, v97
	v_fmac_f32_e32 v80, v132, v96
	v_fmac_f32_e32 v81, v133, v97
	v_fmac_f32_e32 v82, v130, v96
	v_fmac_f32_e32 v83, v131, v97
	v_fmac_f32_e32 v84, v128, v96
	v_fmac_f32_e32 v85, v129, v97
	v_fmac_f32_e32 v86, v126, v96
	v_fmac_f32_e32 v87, v127, v97
	v_fmac_f32_e32 v88, v124, v96
	v_fmac_f32_e32 v89, v125, v97
	s_waitcnt vmcnt(20)
	s_cbranch_vccnz .Lmx_e25
.Lmx_b25:
	v_lshlrev_b32_e32 v98, 16, v218
	v_and_b32_e32 v99, 0xffff0000, v218
	v_fmac_f32_e32 v172, v156, v98
	v_fmac_f32_e32 v173, v157, v99
	v_fmac_f32_e32 v174, v154, v98
	v_fmac_f32_e32 v175, v155, v99
	v_fmac_f32_e32 v176, v152, v98
	v_fmac_f32_e32 v177, v153, v99
	v_fmac_f32_e32 v178, v150, v98
	v_fmac_f32_e32 v179, v151, v99
	v_fmac_f32_e32 v180, v148, v98
	v_fmac_f32_e32 v181, v149, v99
	v_fmac_f32_e32 v182, v146, v98
	v_fmac_f32_e32 v183, v147, v99
	v_fmac_f32_e32 v184, v144, v98
	v_fmac_f32_e32 v185, v145, v99
	v_fmac_f32_e32 v186, v142, v98
	v_fmac_f32_e32 v187, v143, v99
	v_fmac_f32_e32 v188, v140, v98
	v_fmac_f32_e32 v189, v141, v99
	v_fmac_f32_e32 v190, v138, v98
	v_fmac_f32_e32 v191, v139, v99
	v_fmac_f32_e32 v78, v136, v98
	v_fmac_f32_e32 v79, v137, v99
	v_fmac_f32_e32 v80, v134, v98
	v_fmac_f32_e32 v81, v135, v99
	v_fmac_f32_e32 v82, v132, v98
	v_fmac_f32_e32 v83, v133, v99
	v_fmac_f32_e32 v84, v130, v98
	v_fmac_f32_e32 v85, v131, v99
	v_fmac_f32_e32 v86, v128, v98
	v_fmac_f32_e32 v87, v129, v99
	v_fmac_f32_e32 v88, v126, v98
	v_fmac_f32_e32 v89, v127, v99
	s_waitcnt vmcnt(19)
	s_cbranch_vccnz .Lmx_e26
.Lmx_b26:
	v_lshlrev_b32_e32 v96, 16, v219
	v_and_b32_e32 v97, 0xffff0000, v219
	v_fmac_f32_e32 v172, v158, v96
	v_fmac_f32_e32 v173, v159, v97
	v_fmac_f32_e32 v174, v156, v96
	v_fmac_f32_e32 v175, v157, v97
	v_fmac_f32_e32 v176, v154, v96
	v_fmac_f32_e32 v177, v155, v97
	v_fmac_f32_e32 v178, v152, v96
	v_fmac_f32_e32 v179, v153, v97
	v_fmac_f32_e32 v180, v150, v96
	v_fmac_f32_e32 v181, v151, v97
	v_fmac_f32_e32 v182, v148, v96
	v_fmac_f32_e32 v183, v149, v97
	v_fmac_f32_e32 v184, v146, v96
	v_fmac_f32_e32 v185, v147, v97
	v_fmac_f32_e32 v186, v144, v96
	v_fmac_f32_e32 v187, v145, v97
	v_fmac_f32_e32 v188, v142, v96
	v_fmac_f32_e32 v189, v143, v97
	v_fmac_f32_e32 v190, v140, v96
	v_fmac_f32_e32 v191, v141, v97
	v_fmac_f32_e32 v78, v138, v96
	v_fmac_f32_e32 v79, v139, v97
	v_fmac_f32_e32 v80, v136, v96
	v_fmac_f32_e32 v81, v137, v97
	v_fmac_f32_e32 v82, v134, v96
	v_fmac_f32_e32 v83, v135, v97
	v_fmac_f32_e32 v84, v132, v96
	v_fmac_f32_e32 v85, v133, v97
	v_fmac_f32_e32 v86, v130, v96
	v_fmac_f32_e32 v87, v131, v97
	v_fmac_f32_e32 v88, v128, v96
	v_fmac_f32_e32 v89, v129, v97
	s_waitcnt vmcnt(18)
	s_cbranch_vccnz .Lmx_e27
; __device__ __forceinline__ f32x2v bf2(unsigned v) { return (f32x2v){bflo(v), bfhi(v)}; }
; __device__ __forceinline__ void mixer_prompt_run(const Args& p, int run, int c2) {
;     ...
;             for (int i = 0; i < 38; ++i) {
;                 const int ti = t0 + 8 * hh - 30 + i; unsigned v = U32[(rowb + (ti >= 0 ? ti : 0)) * 256 + c2]; v = (ti >= 0) ? v : 0u; const f32x2v x = bf2(v);
; #pragma unroll
;                 for (int t = 0; t < 8; ++t) { const int j = i - t; if (j >= 0 && j <= 30) a[t] = w[j] * x + a[t]; }
;                 if (i == 18) asm volatile("" ::: "memory");
.Lmx_b27:
	v_lshlrev_b32_e32 v98, 16, v220
	v_and_b32_e32 v99, 0xffff0000, v220
	v_fmac_f32_e32 v172, v160, v98
	v_fmac_f32_e32 v173, v161, v99
	v_fmac_f32_e32 v174, v158, v98
	v_fmac_f32_e32 v175, v159, v99
	v_fmac_f32_e32 v176, v156, v98
	v_fmac_f32_e32 v177, v157, v99
	v_fmac_f32_e32 v178, v154, v98
	v_fmac_f32_e32 v179, v155, v99
	v_fmac_f32_e32 v180, v152, v98
	v_fmac_f32_e32 v181, v153, v99
	v_fmac_f32_e32 v182, v150, v98
	v_fmac_f32_e32 v183, v151, v99
	v_fmac_f32_e32 v184, v148, v98
	v_fmac_f32_e32 v185, v149, v99
	v_fmac_f32_e32 v186, v146, v98
	v_fmac_f32_e32 v187, v147, v99
	v_fmac_f32_e32 v188, v144, v98
	v_fmac_f32_e32 v189, v145, v99
	v_fmac_f32_e32 v190, v142, v98
	v_fmac_f32_e32 v191, v143, v99
	v_fmac_f32_e32 v78, v140, v98
	v_fmac_f32_e32 v79, v141, v99
	v_fmac_f32_e32 v80, v138, v98
	v_fmac_f32_e32 v81, v139, v99
	v_fmac_f32_e32 v82, v136, v98
	v_fmac_f32_e32 v83, v137, v99
	v_fmac_f32_e32 v84, v134, v98
	v_fmac_f32_e32 v85, v135, v99
	v_fmac_f32_e32 v86, v132, v98
	v_fmac_f32_e32 v87, v133, v99
	v_fmac_f32_e32 v88, v130, v98
	v_fmac_f32_e32 v89, v131, v99
	s_waitcnt vmcnt(17)
	s_cbranch_vccnz .Lmx_e28
.Lmx_b28:
	v_lshlrev_b32_e32 v96, 16, v221
	v_and_b32_e32 v97, 0xffff0000, v221
	v_fmac_f32_e32 v172, v162, v96
	v_fmac_f32_e32 v173, v163, v97
	v_fmac_f32_e32 v174, v160, v96
	v_fmac_f32_e32 v175, v161, v97
	v_fmac_f32_e32 v176, v158, v96
	v_fmac_f32_e32 v177, v159, v97
	v_fmac_f32_e32 v178, v156, v96
	v_fmac_f32_e32 v179, v157, v97
	v_fmac_f32_e32 v180, v154, v96
	v_fmac_f32_e32 v181, v155, v97
	v_fmac_f32_e32 v182, v152, v96
	v_fmac_f32_e32 v183, v153, v97
	v_fmac_f32_e32 v184, v150, v96
	v_fmac_f32_e32 v185, v151, v97
	v_fmac_f32_e32 v186, v148, v96
	v_fmac_f32_e32 v187, v149, v97
	v_fmac_f32_e32 v188, v146, v96
	v_fmac_f32_e32 v189, v147, v97
	v_fmac_f32_e32 v190, v144, v96
	v_fmac_f32_e32 v191, v145, v97
	v_fmac_f32_e32 v78, v142, v96
	v_fmac_f32_e32 v79, v143, v97
	v_fmac_f32_e32 v80, v140, v96
	v_fmac_f32_e32 v81, v141, v97
	v_fmac_f32_e32 v82, v138, v96
	v_fmac_f32_e32 v83, v139, v97
	v_fmac_f32_e32 v84, v136, v96
	v_fmac_f32_e32 v85, v137, v97
	v_fmac_f32_e32 v86, v134, v96
	v_fmac_f32_e32 v87, v135, v97
	v_fmac_f32_e32 v88, v132, v96
	v_fmac_f32_e32 v89, v133, v97
	s_waitcnt vmcnt(16)
	s_cbranch_vccnz .Lmx_e29
.Lmx_b29:
	v_lshlrev_b32_e32 v98, 16, v222
	v_and_b32_e32 v99, 0xffff0000, v222
	v_fmac_f32_e32 v172, v168, v98
	v_fmac_f32_e32 v173, v169, v99
	v_fmac_f32_e32 v174, v162, v98
	v_fmac_f32_e32 v175, v163, v99
	v_fmac_f32_e32 v176, v160, v98
	v_fmac_f32_e32 v177, v161, v99
	v_fmac_f32_e32 v178, v158, v98
	v_fmac_f32_e32 v179, v159, v99
	v_fmac_f32_e32 v180, v156, v98
	v_fmac_f32_e32 v181, v157, v99
	v_fmac_f32_e32 v182, v154, v98
	v_fmac_f32_e32 v183, v155, v99
	v_fmac_f32_e32 v184, v152, v98
	v_fmac_f32_e32 v185, v153, v99
	v_fmac_f32_e32 v186, v150, v98
	v_fmac_f32_e32 v187, v151, v99
	v_fmac_f32_e32 v188, v148, v98
	v_fmac_f32_e32 v189, v149, v99
	v_fmac_f32_e32 v190, v146, v98
	v_fmac_f32_e32 v191, v147, v99
	v_fmac_f32_e32 v78, v144, v98
	v_fmac_f32_e32 v79, v145, v99
	v_fmac_f32_e32 v80, v142, v98
	v_fmac_f32_e32 v81, v143, v99
	v_fmac_f32_e32 v82, v140, v98
	v_fmac_f32_e32 v83, v141, v99
	v_fmac_f32_e32 v84, v138, v98
	v_fmac_f32_e32 v85, v139, v99
	v_fmac_f32_e32 v86, v136, v98
	v_fmac_f32_e32 v87, v137, v99
	v_fmac_f32_e32 v88, v134, v98
	v_fmac_f32_e32 v89, v135, v99
	s_waitcnt vmcnt(15)
	v_lshlrev_b32_e32 v96, 16, v223
	v_and_b32_e32 v97, 0xffff0000, v223
	v_fmac_f32_e32 v172, v170, v96
	v_fmac_f32_e32 v173, v171, v97
	v_fmac_f32_e32 v174, v168, v96
	v_fmac_f32_e32 v175, v169, v97
	v_fmac_f32_e32 v176, v162, v96
	v_fmac_f32_e32 v177, v163, v97
	v_fmac_f32_e32 v178, v160, v96
	v_fmac_f32_e32 v179, v161, v97
	v_fmac_f32_e32 v180, v158, v96
	v_fmac_f32_e32 v181, v159, v97
	v_fmac_f32_e32 v182, v156, v96
	v_fmac_f32_e32 v183, v157, v97
	v_fmac_f32_e32 v184, v154, v96
	v_fmac_f32_e32 v185, v155, v97
	v_fmac_f32_e32 v186, v152, v96
	v_fmac_f32_e32 v187, v153, v97
	v_fmac_f32_e32 v188, v150, v96
	v_fmac_f32_e32 v189, v151, v97
	v_fmac_f32_e32 v190, v148, v96
	v_fmac_f32_e32 v191, v149, v97
	v_fmac_f32_e32 v78, v146, v96
	v_fmac_f32_e32 v79, v147, v97
	v_fmac_f32_e32 v80, v144, v96
	v_fmac_f32_e32 v81, v145, v97
	v_fmac_f32_e32 v82, v142, v96
	v_fmac_f32_e32 v83, v143, v97
	v_fmac_f32_e32 v84, v140, v96
	v_fmac_f32_e32 v85, v141, v97
	v_fmac_f32_e32 v86, v138, v96
	v_fmac_f32_e32 v87, v139, v97
	v_fmac_f32_e32 v88, v136, v96
	v_fmac_f32_e32 v89, v137, v97
	s_waitcnt vmcnt(14)
	v_lshlrev_b32_e32 v98, 16, v224
	v_and_b32_e32 v99, 0xffff0000, v224
	v_fmac_f32_e32 v174, v170, v98
	v_fmac_f32_e32 v175, v171, v99
	v_fmac_f32_e32 v176, v168, v98
	v_fmac_f32_e32 v177, v169, v99
	v_fmac_f32_e32 v178, v162, v98
	v_fmac_f32_e32 v179, v163, v99
	v_fmac_f32_e32 v180, v160, v98
	v_fmac_f32_e32 v181, v161, v99
	v_fmac_f32_e32 v182, v158, v98
	v_fmac_f32_e32 v183, v159, v99
	v_fmac_f32_e32 v184, v156, v98
	v_fmac_f32_e32 v185, v157, v99
	v_fmac_f32_e32 v186, v154, v98
	v_fmac_f32_e32 v187, v155, v99
	v_fmac_f32_e32 v188, v152, v98
	v_fmac_f32_e32 v189, v153, v99
	v_fmac_f32_e32 v190, v150, v98
	v_fmac_f32_e32 v191, v151, v99
	v_fmac_f32_e32 v78, v148, v98
	v_fmac_f32_e32 v79, v149, v99
	v_fmac_f32_e32 v80, v146, v98
	v_fmac_f32_e32 v81, v147, v99
	v_fmac_f32_e32 v82, v144, v98
	v_fmac_f32_e32 v83, v145, v99
	v_fmac_f32_e32 v84, v142, v98
	v_fmac_f32_e32 v85, v143, v99
	v_fmac_f32_e32 v86, v140, v98
	v_fmac_f32_e32 v87, v141, v99
	v_fmac_f32_e32 v88, v138, v98
	v_fmac_f32_e32 v89, v139, v99
	s_waitcnt vmcnt(13)
; __device__ __forceinline__ f32x2v bf2(unsigned v) { return (f32x2v){bflo(v), bfhi(v)}; }
; __device__ __forceinline__ void mixer_prompt_run(const Args& p, int run, int c2) {
;     ...
;             for (int i = 0; i < 38; ++i) {
;                 const int ti = t0 + 8 * hh - 30 + i; unsigned v = U32[(rowb + (ti >= 0 ? ti : 0)) * 256 + c2]; v = (ti >= 0) ? v : 0u; const f32x2v x = bf2(v);
; #pragma unroll
;                 for (int t = 0; t < 8; ++t) { const int j = i - t; if (j >= 0 && j <= 30) a[t] = w[j] * x + a[t]; }
;                 if (i == 18) asm volatile("" ::: "memory");
;             }
	v_lshlrev_b32_e32 v96, 16, v225
	v_and_b32_e32 v97, 0xffff0000, v225
	v_fmac_f32_e32 v176, v170, v96
	v_fmac_f32_e32 v177, v171, v97
	v_fmac_f32_e32 v178, v168, v96
	v_fmac_f32_e32 v179, v169, v97
	v_fmac_f32_e32 v180, v162, v96
	v_fmac_f32_e32 v181, v163, v97
	v_fmac_f32_e32 v182, v160, v96
	v_fmac_f32_e32 v183, v161, v97
	v_fmac_f32_e32 v184, v158, v96
	v_fmac_f32_e32 v185, v159, v97
	v_fmac_f32_e32 v186, v156, v96
	v_fmac_f32_e32 v187, v157, v97
	v_fmac_f32_e32 v188, v154, v96
	v_fmac_f32_e32 v189, v155, v97
	v_fmac_f32_e32 v190, v152, v96
	v_fmac_f32_e32 v191, v153, v97
	v_fmac_f32_e32 v78, v150, v96
	v_fmac_f32_e32 v79, v151, v97
	v_fmac_f32_e32 v80, v148, v96
	v_fmac_f32_e32 v81, v149, v97
	v_fmac_f32_e32 v82, v146, v96
	v_fmac_f32_e32 v83, v147, v97
	v_fmac_f32_e32 v84, v144, v96
	v_fmac_f32_e32 v85, v145, v97
	v_fmac_f32_e32 v86, v142, v96
	v_fmac_f32_e32 v87, v143, v97
	v_fmac_f32_e32 v88, v140, v96
	v_fmac_f32_e32 v89, v141, v97
	s_waitcnt vmcnt(12)
	v_lshlrev_b32_e32 v98, 16, v226
	v_and_b32_e32 v99, 0xffff0000, v226
	v_fmac_f32_e32 v178, v170, v98
	v_fmac_f32_e32 v179, v171, v99
	v_fmac_f32_e32 v180, v168, v98
	v_fmac_f32_e32 v181, v169, v99
	v_fmac_f32_e32 v182, v162, v98
	v_fmac_f32_e32 v183, v163, v99
	v_fmac_f32_e32 v184, v160, v98
	v_fmac_f32_e32 v185, v161, v99
	v_fmac_f32_e32 v186, v158, v98
	v_fmac_f32_e32 v187, v159, v99
	v_fmac_f32_e32 v188, v156, v98
	v_fmac_f32_e32 v189, v157, v99
	v_fmac_f32_e32 v190, v154, v98
	v_fmac_f32_e32 v191, v155, v99
	v_fmac_f32_e32 v78, v152, v98
	v_fmac_f32_e32 v79, v153, v99
	v_fmac_f32_e32 v80, v150, v98
	v_fmac_f32_e32 v81, v151, v99
	v_fmac_f32_e32 v82, v148, v98
	v_fmac_f32_e32 v83, v149, v99
	v_fmac_f32_e32 v84, v146, v98
	v_fmac_f32_e32 v85, v147, v99
	v_fmac_f32_e32 v86, v144, v98
	v_fmac_f32_e32 v87, v145, v99
	v_fmac_f32_e32 v88, v142, v98
	v_fmac_f32_e32 v89, v143, v99
	s_waitcnt vmcnt(11)
	v_lshlrev_b32_e32 v96, 16, v227
	v_and_b32_e32 v97, 0xffff0000, v227
	v_fmac_f32_e32 v180, v170, v96
	v_fmac_f32_e32 v181, v171, v97
	v_fmac_f32_e32 v182, v168, v96
	v_fmac_f32_e32 v183, v169, v97
	v_fmac_f32_e32 v184, v162, v96
	v_fmac_f32_e32 v185, v163, v97
	v_fmac_f32_e32 v186, v160, v96
	v_fmac_f32_e32 v187, v161, v97
	v_fmac_f32_e32 v188, v158, v96
	v_fmac_f32_e32 v189, v159, v97
	v_fmac_f32_e32 v190, v156, v96
	v_fmac_f32_e32 v191, v157, v97
	v_fmac_f32_e32 v78, v154, v96
	v_fmac_f32_e32 v79, v155, v97
	v_fmac_f32_e32 v80, v152, v96
	v_fmac_f32_e32 v81, v153, v97
	v_fmac_f32_e32 v82, v150, v96
	v_fmac_f32_e32 v83, v151, v97
	v_fmac_f32_e32 v84, v148, v96
	v_fmac_f32_e32 v85, v149, v97
	v_fmac_f32_e32 v86, v146, v96
	v_fmac_f32_e32 v87, v147, v97
	v_fmac_f32_e32 v88, v144, v96
	v_fmac_f32_e32 v89, v145, v97
	s_waitcnt vmcnt(10)
	v_lshlrev_b32_e32 v98, 16, v228
	v_and_b32_e32 v99, 0xffff0000, v228
	v_fmac_f32_e32 v182, v170, v98
	v_fmac_f32_e32 v183, v171, v99
	v_fmac_f32_e32 v184, v168, v98
	v_fmac_f32_e32 v185, v169, v99
	v_fmac_f32_e32 v186, v162, v98
	v_fmac_f32_e32 v187, v163, v99
	v_fmac_f32_e32 v188, v160, v98
	v_fmac_f32_e32 v189, v161, v99
	v_fmac_f32_e32 v190, v158, v98
	v_fmac_f32_e32 v191, v159, v99
	v_fmac_f32_e32 v78, v156, v98
	v_fmac_f32_e32 v79, v157, v99
	v_fmac_f32_e32 v80, v154, v98
	v_fmac_f32_e32 v81, v155, v99
	v_fmac_f32_e32 v82, v152, v98
	v_fmac_f32_e32 v83, v153, v99
	v_fmac_f32_e32 v84, v150, v98
	v_fmac_f32_e32 v85, v151, v99
	v_fmac_f32_e32 v86, v148, v98
	v_fmac_f32_e32 v87, v149, v99
	v_fmac_f32_e32 v88, v146, v98
	v_fmac_f32_e32 v89, v147, v99
	s_waitcnt vmcnt(9)
	v_lshlrev_b32_e32 v96, 16, v229
	v_and_b32_e32 v97, 0xffff0000, v229
	v_fmac_f32_e32 v184, v170, v96
	v_fmac_f32_e32 v185, v171, v97
	v_fmac_f32_e32 v186, v168, v96
	v_fmac_f32_e32 v187, v169, v97
	v_fmac_f32_e32 v188, v162, v96
	v_fmac_f32_e32 v189, v163, v97
	v_fmac_f32_e32 v190, v160, v96
	v_fmac_f32_e32 v191, v161, v97
	v_fmac_f32_e32 v78, v158, v96
	v_fmac_f32_e32 v79, v159, v97
	v_fmac_f32_e32 v80, v156, v96
	v_fmac_f32_e32 v81, v157, v97
	v_fmac_f32_e32 v82, v154, v96
	v_fmac_f32_e32 v83, v155, v97
	v_fmac_f32_e32 v84, v152, v96
	v_fmac_f32_e32 v85, v153, v97
	v_fmac_f32_e32 v86, v150, v96
	v_fmac_f32_e32 v87, v151, v97
	v_fmac_f32_e32 v88, v148, v96
	v_fmac_f32_e32 v89, v149, v97
	s_waitcnt vmcnt(8)
	v_lshlrev_b32_e32 v98, 16, v230
	v_and_b32_e32 v99, 0xffff0000, v230
	v_fmac_f32_e32 v186, v170, v98
	v_fmac_f32_e32 v187, v171, v99
	v_fmac_f32_e32 v188, v168, v98
	v_fmac_f32_e32 v189, v169, v99
	v_fmac_f32_e32 v190, v162, v98
	v_fmac_f32_e32 v191, v163, v99
	v_fmac_f32_e32 v78, v160, v98
	v_fmac_f32_e32 v79, v161, v99
	v_fmac_f32_e32 v80, v158, v98
	v_fmac_f32_e32 v81, v159, v99
	v_fmac_f32_e32 v82, v156, v98
	v_fmac_f32_e32 v83, v157, v99
	v_fmac_f32_e32 v84, v154, v98
	v_fmac_f32_e32 v85, v155, v99
	v_fmac_f32_e32 v86, v152, v98
	v_fmac_f32_e32 v87, v153, v99
	v_fmac_f32_e32 v88, v150, v98
	v_fmac_f32_e32 v89, v151, v99
	s_waitcnt vmcnt(7)
	v_lshlrev_b32_e32 v96, 16, v231
	v_and_b32_e32 v97, 0xffff0000, v231
	v_fmac_f32_e32 v188, v170, v96
	v_fmac_f32_e32 v189, v171, v97
	v_fmac_f32_e32 v190, v168, v96
	v_fmac_f32_e32 v191, v169, v97
	v_fmac_f32_e32 v78, v162, v96
	v_fmac_f32_e32 v79, v163, v97
	v_fmac_f32_e32 v80, v160, v96
	v_fmac_f32_e32 v81, v161, v97
	v_fmac_f32_e32 v82, v158, v96
	v_fmac_f32_e32 v83, v159, v97
	v_fmac_f32_e32 v84, v156, v96
	v_fmac_f32_e32 v85, v157, v97
	v_fmac_f32_e32 v86, v154, v96
	v_fmac_f32_e32 v87, v155, v97
	v_fmac_f32_e32 v88, v152, v96
	v_fmac_f32_e32 v89, v153, v97
	s_waitcnt vmcnt(6)
; template <int CTRL> __device__ __forceinline__ float dpp_mov(float v) { return __builtin_bit_cast(float, __builtin_amdgcn_update_dpp(0, __builtin_bit_cast(int, v), CTRL, 0xf, 0xf, true)); }
; __device__ __forceinline__ f32x2v bf2(unsigned v) { return (f32x2v){bflo(v), bfhi(v)}; }
; __device__ __forceinline__ float half_wave_sum(float v) {
;     v += dpp_mov<0xB1>(v);
;     v += dpp_mov<0x4E>(v);
;     v += dpp_mov<0x141>(v);
;     v += dpp_mov<0x140>(v);
;     v += __shfl_xor(v, 16);
;     return v;
; }
; __device__ __forceinline__ void gn_swish_store(float v0, float v1, f32x2v gg, f32x2v gb, unsigned* dst) {
;     const float mean = half_wave_sum(v0 + v1) * (1.0f / 64.0f); const float d0 = v0 - mean, d1 = v1 - mean;
; __device__ __forceinline__ void mixer_prompt_run(const Args& p, int run, int c2) {
;     ...
;             for (int i = 0; i < 38; ++i) {
;                 const int ti = t0 + 8 * hh - 30 + i; unsigned v = U32[(rowb + (ti >= 0 ? ti : 0)) * 256 + c2]; v = (ti >= 0) ? v : 0u; const f32x2v x = bf2(v);
; #pragma unroll
;                 for (int t = 0; t < 8; ++t) { const int j = i - t; if (j >= 0 && j <= 30) a[t] = w[j] * x + a[t]; }
;                 if (i == 18) asm volatile("" ::: "memory");
;             }
	v_lshlrev_b32_e32 v98, 16, v232
	v_and_b32_e32 v99, 0xffff0000, v232
	v_fmac_f32_e32 v190, v170, v98
	v_fmac_f32_e32 v191, v171, v99
	v_fmac_f32_e32 v78, v168, v98
	v_fmac_f32_e32 v79, v169, v99
	v_fmac_f32_e32 v80, v162, v98
	v_fmac_f32_e32 v81, v163, v99
	v_fmac_f32_e32 v82, v160, v98
	v_fmac_f32_e32 v83, v161, v99
	v_fmac_f32_e32 v84, v158, v98
	v_fmac_f32_e32 v85, v159, v99
	v_fmac_f32_e32 v86, v156, v98
	v_fmac_f32_e32 v87, v157, v99
	v_fmac_f32_e32 v88, v154, v98
	v_fmac_f32_e32 v89, v155, v99
	s_waitcnt vmcnt(5)
	v_lshlrev_b32_e32 v96, 16, v233
	v_and_b32_e32 v97, 0xffff0000, v233
	v_fmac_f32_e32 v78, v170, v96
	v_fmac_f32_e32 v79, v171, v97
	v_fmac_f32_e32 v80, v168, v96
	v_fmac_f32_e32 v81, v169, v97
	v_fmac_f32_e32 v82, v162, v96
	v_fmac_f32_e32 v83, v163, v97
	v_fmac_f32_e32 v84, v160, v96
	v_fmac_f32_e32 v85, v161, v97
	v_fmac_f32_e32 v86, v158, v96
	v_fmac_f32_e32 v87, v159, v97
	v_fmac_f32_e32 v88, v156, v96
	v_fmac_f32_e32 v89, v157, v97
	s_waitcnt vmcnt(4)
	v_lshlrev_b32_e32 v98, 16, v234
	v_and_b32_e32 v99, 0xffff0000, v234
	v_fmac_f32_e32 v80, v170, v98
	v_fmac_f32_e32 v81, v171, v99
	v_fmac_f32_e32 v82, v168, v98
	v_fmac_f32_e32 v83, v169, v99
	v_fmac_f32_e32 v84, v162, v98
	v_fmac_f32_e32 v85, v163, v99
	v_fmac_f32_e32 v86, v160, v98
	v_fmac_f32_e32 v87, v161, v99
	v_fmac_f32_e32 v88, v158, v98
	v_fmac_f32_e32 v89, v159, v99
	s_waitcnt vmcnt(3)
	v_lshlrev_b32_e32 v96, 16, v235
	v_and_b32_e32 v97, 0xffff0000, v235
	v_fmac_f32_e32 v82, v170, v96
	v_fmac_f32_e32 v83, v171, v97
	v_fmac_f32_e32 v84, v168, v96
	v_fmac_f32_e32 v85, v169, v97
	v_fmac_f32_e32 v86, v162, v96
	v_fmac_f32_e32 v87, v163, v97
	v_fmac_f32_e32 v88, v160, v96
	v_fmac_f32_e32 v89, v161, v97
	s_waitcnt vmcnt(2)
	v_lshlrev_b32_e32 v98, 16, v236
	v_and_b32_e32 v99, 0xffff0000, v236
	v_fmac_f32_e32 v84, v170, v98
	v_fmac_f32_e32 v85, v171, v99
	v_fmac_f32_e32 v86, v168, v98
	v_fmac_f32_e32 v87, v169, v99
	v_fmac_f32_e32 v88, v162, v98
	v_fmac_f32_e32 v89, v163, v99
	s_waitcnt vmcnt(1)
	v_lshlrev_b32_e32 v96, 16, v237
	v_and_b32_e32 v97, 0xffff0000, v237
	v_fmac_f32_e32 v86, v170, v96
	v_fmac_f32_e32 v87, v171, v97
	v_fmac_f32_e32 v88, v168, v96
	v_fmac_f32_e32 v89, v169, v97
	s_waitcnt vmcnt(0)
	v_lshlrev_b32_e32 v98, 16, v238
	v_and_b32_e32 v99, 0xffff0000, v238
	v_fmac_f32_e32 v88, v170, v98
	v_fmac_f32_e32 v89, v171, v99
	v_add_f32_e32 v194, v172, v173
	v_add_f32_e32 v198, v174, v175
	v_add_f32_e32 v202, v176, v177
	v_add_f32_e32 v206, v178, v179
	v_add_f32_e32 v210, v180, v181
	v_add_f32_e32 v214, v182, v183
	v_add_f32_e32 v218, v184, v185
	v_add_f32_e32 v222, v186, v187
	v_add_f32_dpp v194, v194, v194 quad_perm:[1,0,3,2] row_mask:0xf bank_mask:0xf bound_ctrl:1
	v_add_f32_dpp v198, v198, v198 quad_perm:[1,0,3,2] row_mask:0xf bank_mask:0xf bound_ctrl:1
	v_add_f32_dpp v202, v202, v202 quad_perm:[1,0,3,2] row_mask:0xf bank_mask:0xf bound_ctrl:1
	v_add_f32_dpp v206, v206, v206 quad_perm:[1,0,3,2] row_mask:0xf bank_mask:0xf bound_ctrl:1
	v_add_f32_dpp v210, v210, v210 quad_perm:[1,0,3,2] row_mask:0xf bank_mask:0xf bound_ctrl:1
	v_add_f32_dpp v214, v214, v214 quad_perm:[1,0,3,2] row_mask:0xf bank_mask:0xf bound_ctrl:1
	v_add_f32_dpp v218, v218, v218 quad_perm:[1,0,3,2] row_mask:0xf bank_mask:0xf bound_ctrl:1
	v_add_f32_dpp v222, v222, v222 quad_perm:[1,0,3,2] row_mask:0xf bank_mask:0xf bound_ctrl:1
	v_add_f32_dpp v194, v194, v194 quad_perm:[2,3,0,1] row_mask:0xf bank_mask:0xf bound_ctrl:1
	v_add_f32_dpp v198, v198, v198 quad_perm:[2,3,0,1] row_mask:0xf bank_mask:0xf bound_ctrl:1
	v_add_f32_dpp v202, v202, v202 quad_perm:[2,3,0,1] row_mask:0xf bank_mask:0xf bound_ctrl:1
	v_add_f32_dpp v206, v206, v206 quad_perm:[2,3,0,1] row_mask:0xf bank_mask:0xf bound_ctrl:1
	v_add_f32_dpp v210, v210, v210 quad_perm:[2,3,0,1] row_mask:0xf bank_mask:0xf bound_ctrl:1
	v_add_f32_dpp v214, v214, v214 quad_perm:[2,3,0,1] row_mask:0xf bank_mask:0xf bound_ctrl:1
	v_add_f32_dpp v218, v218, v218 quad_perm:[2,3,0,1] row_mask:0xf bank_mask:0xf bound_ctrl:1
	v_add_f32_dpp v222, v222, v222 quad_perm:[2,3,0,1] row_mask:0xf bank_mask:0xf bound_ctrl:1
	v_add_f32_dpp v194, v194, v194 row_half_mirror row_mask:0xf bank_mask:0xf bound_ctrl:1
	v_add_f32_dpp v198, v198, v198 row_half_mirror row_mask:0xf bank_mask:0xf bound_ctrl:1
	v_add_f32_dpp v202, v202, v202 row_half_mirror row_mask:0xf bank_mask:0xf bound_ctrl:1
	v_add_f32_dpp v206, v206, v206 row_half_mirror row_mask:0xf bank_mask:0xf bound_ctrl:1
	v_add_f32_dpp v210, v210, v210 row_half_mirror row_mask:0xf bank_mask:0xf bound_ctrl:1
	v_add_f32_dpp v214, v214, v214 row_half_mirror row_mask:0xf bank_mask:0xf bound_ctrl:1
	v_add_f32_dpp v218, v218, v218 row_half_mirror row_mask:0xf bank_mask:0xf bound_ctrl:1
	v_add_f32_dpp v222, v222, v222 row_half_mirror row_mask:0xf bank_mask:0xf bound_ctrl:1
	v_add_f32_dpp v194, v194, v194 row_mirror row_mask:0xf bank_mask:0xf bound_ctrl:1
	v_add_f32_dpp v198, v198, v198 row_mirror row_mask:0xf bank_mask:0xf bound_ctrl:1
	v_add_f32_dpp v202, v202, v202 row_mirror row_mask:0xf bank_mask:0xf bound_ctrl:1
	v_add_f32_dpp v206, v206, v206 row_mirror row_mask:0xf bank_mask:0xf bound_ctrl:1
	v_add_f32_dpp v210, v210, v210 row_mirror row_mask:0xf bank_mask:0xf bound_ctrl:1
	v_add_f32_dpp v214, v214, v214 row_mirror row_mask:0xf bank_mask:0xf bound_ctrl:1
	v_add_f32_dpp v218, v218, v218 row_mirror row_mask:0xf bank_mask:0xf bound_ctrl:1
	v_add_f32_dpp v222, v222, v222 row_mirror row_mask:0xf bank_mask:0xf bound_ctrl:1
	ds_bpermute_b32 v195, v239, v194
	ds_bpermute_b32 v199, v239, v198
	ds_bpermute_b32 v203, v239, v202
	ds_bpermute_b32 v207, v239, v206
	ds_bpermute_b32 v211, v239, v210
	ds_bpermute_b32 v215, v239, v214
	ds_bpermute_b32 v219, v239, v218
	ds_bpermute_b32 v223, v239, v222
	s_waitcnt lgkmcnt(7)
; template <int CTRL> __device__ __forceinline__ float dpp_mov(float v) { return __builtin_bit_cast(float, __builtin_amdgcn_update_dpp(0, __builtin_bit_cast(int, v), CTRL, 0xf, 0xf, true)); }
; __device__ __forceinline__ float half_wave_sum(float v) {
;     v += dpp_mov<0xB1>(v);
;     v += dpp_mov<0x4E>(v);
;     v += dpp_mov<0x141>(v);
;     v += dpp_mov<0x140>(v);
;     v += __shfl_xor(v, 16);
;     return v;
; }
; __device__ __forceinline__ void gn_swish_store(float v0, float v1, f32x2v gg, f32x2v gb, unsigned* dst) {
;     const float mean = half_wave_sum(v0 + v1) * (1.0f / 64.0f); const float d0 = v0 - mean, d1 = v1 - mean;
;     const float rstd = rsqrtf(half_wave_sum(d0 * d0 + d1 * d1) * (1.0f / 64.0f) + LN_EPS);
	v_add_f32_e32 v194, v194, v195
	s_waitcnt lgkmcnt(6)
	v_add_f32_e32 v198, v198, v199
	s_waitcnt lgkmcnt(5)
	v_add_f32_e32 v202, v202, v203
	s_waitcnt lgkmcnt(4)
	v_add_f32_e32 v206, v206, v207
	s_waitcnt lgkmcnt(3)
	v_add_f32_e32 v210, v210, v211
	s_waitcnt lgkmcnt(2)
	v_add_f32_e32 v214, v214, v215
	s_waitcnt lgkmcnt(1)
	v_add_f32_e32 v218, v218, v219
	s_waitcnt lgkmcnt(0)
	v_add_f32_e32 v222, v222, v223
	v_mul_f32_e32 v194, 0x3c800000, v194
	v_mul_f32_e32 v198, 0x3c800000, v198
	v_mul_f32_e32 v202, 0x3c800000, v202
	v_mul_f32_e32 v206, 0x3c800000, v206
	v_mul_f32_e32 v210, 0x3c800000, v210
	v_mul_f32_e32 v214, 0x3c800000, v214
	v_mul_f32_e32 v218, 0x3c800000, v218
	v_mul_f32_e32 v222, 0x3c800000, v222
	v_pk_add_f32 v[172:173], v[172:173], v[194:195] op_sel_hi:[1,0] neg_lo:[0,1] neg_hi:[0,1]
	v_pk_add_f32 v[174:175], v[174:175], v[198:199] op_sel_hi:[1,0] neg_lo:[0,1] neg_hi:[0,1]
	v_pk_add_f32 v[176:177], v[176:177], v[202:203] op_sel_hi:[1,0] neg_lo:[0,1] neg_hi:[0,1]
	v_pk_add_f32 v[178:179], v[178:179], v[206:207] op_sel_hi:[1,0] neg_lo:[0,1] neg_hi:[0,1]
	v_pk_add_f32 v[180:181], v[180:181], v[210:211] op_sel_hi:[1,0] neg_lo:[0,1] neg_hi:[0,1]
	v_pk_add_f32 v[182:183], v[182:183], v[214:215] op_sel_hi:[1,0] neg_lo:[0,1] neg_hi:[0,1]
	v_pk_add_f32 v[184:185], v[184:185], v[218:219] op_sel_hi:[1,0] neg_lo:[0,1] neg_hi:[0,1]
	v_pk_add_f32 v[186:187], v[186:187], v[222:223] op_sel_hi:[1,0] neg_lo:[0,1] neg_hi:[0,1]
	v_pk_mul_f32 v[196:197], v[172:173], v[172:173]
	v_pk_mul_f32 v[200:201], v[174:175], v[174:175]
	v_pk_mul_f32 v[204:205], v[176:177], v[176:177]
	v_pk_mul_f32 v[208:209], v[178:179], v[178:179]
	v_pk_mul_f32 v[212:213], v[180:181], v[180:181]
	v_pk_mul_f32 v[216:217], v[182:183], v[182:183]
	v_pk_mul_f32 v[220:221], v[184:185], v[184:185]
	v_pk_mul_f32 v[224:225], v[186:187], v[186:187]
	v_add_f32_e32 v194, v196, v197
	v_add_f32_e32 v198, v200, v201
	v_add_f32_e32 v202, v204, v205
	v_add_f32_e32 v206, v208, v209
	v_add_f32_e32 v210, v212, v213
	v_add_f32_e32 v214, v216, v217
	v_add_f32_e32 v218, v220, v221
	v_add_f32_e32 v222, v224, v225
	v_add_f32_dpp v194, v194, v194 quad_perm:[1,0,3,2] row_mask:0xf bank_mask:0xf bound_ctrl:1
	v_add_f32_dpp v198, v198, v198 quad_perm:[1,0,3,2] row_mask:0xf bank_mask:0xf bound_ctrl:1
	v_add_f32_dpp v202, v202, v202 quad_perm:[1,0,3,2] row_mask:0xf bank_mask:0xf bound_ctrl:1
	v_add_f32_dpp v206, v206, v206 quad_perm:[1,0,3,2] row_mask:0xf bank_mask:0xf bound_ctrl:1
	v_add_f32_dpp v210, v210, v210 quad_perm:[1,0,3,2] row_mask:0xf bank_mask:0xf bound_ctrl:1
	v_add_f32_dpp v214, v214, v214 quad_perm:[1,0,3,2] row_mask:0xf bank_mask:0xf bound_ctrl:1
	v_add_f32_dpp v218, v218, v218 quad_perm:[1,0,3,2] row_mask:0xf bank_mask:0xf bound_ctrl:1
	v_add_f32_dpp v222, v222, v222 quad_perm:[1,0,3,2] row_mask:0xf bank_mask:0xf bound_ctrl:1
	v_add_f32_dpp v194, v194, v194 quad_perm:[2,3,0,1] row_mask:0xf bank_mask:0xf bound_ctrl:1
	v_add_f32_dpp v198, v198, v198 quad_perm:[2,3,0,1] row_mask:0xf bank_mask:0xf bound_ctrl:1
	v_add_f32_dpp v202, v202, v202 quad_perm:[2,3,0,1] row_mask:0xf bank_mask:0xf bound_ctrl:1
	v_add_f32_dpp v206, v206, v206 quad_perm:[2,3,0,1] row_mask:0xf bank_mask:0xf bound_ctrl:1
	v_add_f32_dpp v210, v210, v210 quad_perm:[2,3,0,1] row_mask:0xf bank_mask:0xf bound_ctrl:1
	v_add_f32_dpp v214, v214, v214 quad_perm:[2,3,0,1] row_mask:0xf bank_mask:0xf bound_ctrl:1
	v_add_f32_dpp v218, v218, v218 quad_perm:[2,3,0,1] row_mask:0xf bank_mask:0xf bound_ctrl:1
	v_add_f32_dpp v222, v222, v222 quad_perm:[2,3,0,1] row_mask:0xf bank_mask:0xf bound_ctrl:1
	v_add_f32_dpp v194, v194, v194 row_half_mirror row_mask:0xf bank_mask:0xf bound_ctrl:1
	v_add_f32_dpp v198, v198, v198 row_half_mirror row_mask:0xf bank_mask:0xf bound_ctrl:1
	v_add_f32_dpp v202, v202, v202 row_half_mirror row_mask:0xf bank_mask:0xf bound_ctrl:1
	v_add_f32_dpp v206, v206, v206 row_half_mirror row_mask:0xf bank_mask:0xf bound_ctrl:1
	v_add_f32_dpp v210, v210, v210 row_half_mirror row_mask:0xf bank_mask:0xf bound_ctrl:1
	v_add_f32_dpp v214, v214, v214 row_half_mirror row_mask:0xf bank_mask:0xf bound_ctrl:1
	v_add_f32_dpp v218, v218, v218 row_half_mirror row_mask:0xf bank_mask:0xf bound_ctrl:1
	v_add_f32_dpp v222, v222, v222 row_half_mirror row_mask:0xf bank_mask:0xf bound_ctrl:1
	v_add_f32_dpp v194, v194, v194 row_mirror row_mask:0xf bank_mask:0xf bound_ctrl:1
	v_add_f32_dpp v198, v198, v198 row_mirror row_mask:0xf bank_mask:0xf bound_ctrl:1
	v_add_f32_dpp v202, v202, v202 row_mirror row_mask:0xf bank_mask:0xf bound_ctrl:1
	v_add_f32_dpp v206, v206, v206 row_mirror row_mask:0xf bank_mask:0xf bound_ctrl:1
	v_add_f32_dpp v210, v210, v210 row_mirror row_mask:0xf bank_mask:0xf bound_ctrl:1
	v_add_f32_dpp v214, v214, v214 row_mirror row_mask:0xf bank_mask:0xf bound_ctrl:1
	v_add_f32_dpp v218, v218, v218 row_mirror row_mask:0xf bank_mask:0xf bound_ctrl:1
	v_add_f32_dpp v222, v222, v222 row_mirror row_mask:0xf bank_mask:0xf bound_ctrl:1
	ds_bpermute_b32 v195, v239, v194
	ds_bpermute_b32 v199, v239, v198
	ds_bpermute_b32 v203, v239, v202
	ds_bpermute_b32 v207, v239, v206
	ds_bpermute_b32 v211, v239, v210
	ds_bpermute_b32 v215, v239, v214
	ds_bpermute_b32 v219, v239, v218
	ds_bpermute_b32 v223, v239, v222
	s_waitcnt lgkmcnt(7)
	v_add_f32_e32 v194, v194, v195
	s_waitcnt lgkmcnt(6)
	v_add_f32_e32 v198, v198, v199
	s_waitcnt lgkmcnt(5)
	v_add_f32_e32 v202, v202, v203
	s_waitcnt lgkmcnt(4)
	v_add_f32_e32 v206, v206, v207
	s_waitcnt lgkmcnt(3)
	v_add_f32_e32 v210, v210, v211
	s_waitcnt lgkmcnt(2)
	v_add_f32_e32 v214, v214, v215
	s_waitcnt lgkmcnt(1)
	v_add_f32_e32 v218, v218, v219
	s_waitcnt lgkmcnt(0)
; __device__ __forceinline__ unsigned pk2(float lo, float hi) { f32x2v v = {lo, hi}; b16x2v b = __builtin_convertvector(v, b16x2v); return __builtin_bit_cast(unsigned, b); }
; __device__ __forceinline__ float fsigmoid(float x) { return __builtin_amdgcn_rcpf(1.0f + __expf(-x)); }
; __device__ __forceinline__ void gn_swish_store(float v0, float v1, f32x2v gg, f32x2v gb, unsigned* dst) {
;     const float mean = half_wave_sum(v0 + v1) * (1.0f / 64.0f); const float d0 = v0 - mean, d1 = v1 - mean;
;     const float rstd = rsqrtf(half_wave_sum(d0 * d0 + d1 * d1) * (1.0f / 64.0f) + LN_EPS);
;     float y0 = d0 * rstd * gg.x + gb.x, y1 = d1 * rstd * gg.y + gb.y;
;     y0 = y0 * fsigmoid(y0); y1 = y1 * fsigmoid(y1);
;     *dst = pk2(y0, y1);
; }
; __device__ __forceinline__ void mixer_prompt_run(const Args& p, int run, int c2) {
;     ...
;             for (int t = 0; t < 8; ++t) gn_swish_store(a[t].x, a[t].y, gg, gb, M32 + (rowb + t0 + 8 * hh + t) * 512 + c2);
	v_add_f32_e32 v222, v222, v223
	v_mul_f32_e32 v194, 0x3c800000, v194
	v_mul_f32_e32 v198, 0x3c800000, v198
	v_mul_f32_e32 v202, 0x3c800000, v202
	v_mul_f32_e32 v206, 0x3c800000, v206
	v_mul_f32_e32 v210, 0x3c800000, v210
	v_mul_f32_e32 v214, 0x3c800000, v214
	v_mul_f32_e32 v218, 0x3c800000, v218
	v_mul_f32_e32 v222, 0x3c800000, v222
	v_add_f32_e32 v194, 0x3727c5ac, v194
	v_add_f32_e32 v198, 0x3727c5ac, v198
	v_add_f32_e32 v202, 0x3727c5ac, v202
	v_add_f32_e32 v206, 0x3727c5ac, v206
	v_add_f32_e32 v210, 0x3727c5ac, v210
	v_add_f32_e32 v214, 0x3727c5ac, v214
	v_add_f32_e32 v218, 0x3727c5ac, v218
	v_add_f32_e32 v222, 0x3727c5ac, v222
	v_rsq_f32_e32 v194, v194
	v_rsq_f32_e32 v198, v198
	v_rsq_f32_e32 v202, v202
	v_rsq_f32_e32 v206, v206
	v_rsq_f32_e32 v210, v210
	v_rsq_f32_e32 v214, v214
	v_rsq_f32_e32 v218, v218
	v_rsq_f32_e32 v222, v222
	v_pk_mul_f32 v[172:173], v[172:173], v[194:195] op_sel_hi:[1,0]
	v_pk_mul_f32 v[174:175], v[174:175], v[198:199] op_sel_hi:[1,0]
	v_pk_mul_f32 v[176:177], v[176:177], v[202:203] op_sel_hi:[1,0]
	v_pk_mul_f32 v[178:179], v[178:179], v[206:207] op_sel_hi:[1,0]
	v_pk_mul_f32 v[180:181], v[180:181], v[210:211] op_sel_hi:[1,0]
	v_pk_mul_f32 v[182:183], v[182:183], v[214:215] op_sel_hi:[1,0]
	v_pk_mul_f32 v[184:185], v[184:185], v[218:219] op_sel_hi:[1,0]
	v_pk_mul_f32 v[186:187], v[186:187], v[222:223] op_sel_hi:[1,0]
	v_pk_fma_f32 v[172:173], v[172:173], v[92:93], v[94:95]
	v_pk_fma_f32 v[174:175], v[174:175], v[92:93], v[94:95]
	v_pk_fma_f32 v[176:177], v[176:177], v[92:93], v[94:95]
	v_pk_fma_f32 v[178:179], v[178:179], v[92:93], v[94:95]
	v_pk_fma_f32 v[180:181], v[180:181], v[92:93], v[94:95]
	v_pk_fma_f32 v[182:183], v[182:183], v[92:93], v[94:95]
	v_pk_fma_f32 v[184:185], v[184:185], v[92:93], v[94:95]
	v_pk_fma_f32 v[186:187], v[186:187], v[92:93], v[94:95]
	v_mul_f32_e32 v196, 0xbfb8aa3b, v172
	v_mul_f32_e32 v197, 0xbfb8aa3b, v173
	v_mul_f32_e32 v200, 0xbfb8aa3b, v174
	v_mul_f32_e32 v201, 0xbfb8aa3b, v175
	v_mul_f32_e32 v204, 0xbfb8aa3b, v176
	v_mul_f32_e32 v205, 0xbfb8aa3b, v177
	v_mul_f32_e32 v208, 0xbfb8aa3b, v178
	v_mul_f32_e32 v209, 0xbfb8aa3b, v179
	v_mul_f32_e32 v212, 0xbfb8aa3b, v180
	v_mul_f32_e32 v213, 0xbfb8aa3b, v181
	v_mul_f32_e32 v216, 0xbfb8aa3b, v182
	v_mul_f32_e32 v217, 0xbfb8aa3b, v183
	v_mul_f32_e32 v220, 0xbfb8aa3b, v184
	v_mul_f32_e32 v221, 0xbfb8aa3b, v185
	v_mul_f32_e32 v224, 0xbfb8aa3b, v186
	v_mul_f32_e32 v225, 0xbfb8aa3b, v187
	v_exp_f32_e32 v196, v196
	v_exp_f32_e32 v197, v197
	v_exp_f32_e32 v200, v200
	v_exp_f32_e32 v201, v201
	v_exp_f32_e32 v204, v204
	v_exp_f32_e32 v205, v205
	v_exp_f32_e32 v208, v208
	v_exp_f32_e32 v209, v209
	v_exp_f32_e32 v212, v212
	v_exp_f32_e32 v213, v213
	v_exp_f32_e32 v216, v216
	v_exp_f32_e32 v217, v217
	v_exp_f32_e32 v220, v220
	v_exp_f32_e32 v221, v221
	v_exp_f32_e32 v224, v224
	v_exp_f32_e32 v225, v225
	v_add_f32_e32 v196, 1.0, v196
	v_add_f32_e32 v197, 1.0, v197
	v_add_f32_e32 v200, 1.0, v200
	v_add_f32_e32 v201, 1.0, v201
	v_add_f32_e32 v204, 1.0, v204
	v_add_f32_e32 v205, 1.0, v205
	v_add_f32_e32 v208, 1.0, v208
	v_add_f32_e32 v209, 1.0, v209
	v_add_f32_e32 v212, 1.0, v212
	v_add_f32_e32 v213, 1.0, v213
	v_add_f32_e32 v216, 1.0, v216
	v_add_f32_e32 v217, 1.0, v217
	v_add_f32_e32 v220, 1.0, v220
	v_add_f32_e32 v221, 1.0, v221
	v_add_f32_e32 v224, 1.0, v224
	v_add_f32_e32 v225, 1.0, v225
	v_rcp_f32_e32 v196, v196
	v_rcp_f32_e32 v197, v197
	v_rcp_f32_e32 v200, v200
	v_rcp_f32_e32 v201, v201
	v_rcp_f32_e32 v204, v204
	v_rcp_f32_e32 v205, v205
	v_rcp_f32_e32 v208, v208
	v_rcp_f32_e32 v209, v209
	v_rcp_f32_e32 v212, v212
	v_rcp_f32_e32 v213, v213
	v_rcp_f32_e32 v216, v216
	v_rcp_f32_e32 v217, v217
	v_rcp_f32_e32 v220, v220
	v_rcp_f32_e32 v221, v221
	v_rcp_f32_e32 v224, v224
	v_rcp_f32_e32 v225, v225
	v_pk_mul_f32 v[172:173], v[172:173], v[196:197]
	v_pk_mul_f32 v[174:175], v[174:175], v[200:201]
	v_pk_mul_f32 v[176:177], v[176:177], v[204:205]
	v_pk_mul_f32 v[178:179], v[178:179], v[208:209]
	v_pk_mul_f32 v[180:181], v[180:181], v[212:213]
	v_pk_mul_f32 v[182:183], v[182:183], v[216:217]
	v_pk_mul_f32 v[184:185], v[184:185], v[220:221]
	v_pk_mul_f32 v[186:187], v[186:187], v[224:225]
	v_cvt_pk_bf16_f32 v194, v172, v173
	v_cvt_pk_bf16_f32 v198, v174, v175
	v_cvt_pk_bf16_f32 v202, v176, v177
	v_cvt_pk_bf16_f32 v206, v178, v179
	v_cvt_pk_bf16_f32 v210, v180, v181
	v_cvt_pk_bf16_f32 v214, v182, v183
	v_cvt_pk_bf16_f32 v218, v184, v185
	v_cvt_pk_bf16_f32 v222, v186, v187
	global_store_dword v105, v194, s[70:71] offset:-4096
	global_store_dword v105, v198, s[70:71] offset:-2048
	global_store_dword v105, v202, s[70:71] offset:0
	global_store_dword v105, v206, s[70:71] offset:2048
	s_add_u32 s70, s70, 0x2000
	s_addc_u32 s71, s71, 0
	global_store_dword v105, v210, s[70:71] offset:-4096
	global_store_dword v105, v214, s[70:71] offset:-2048
	global_store_dword v105, v218, s[70:71] offset:0
	global_store_dword v105, v222, s[70:71] offset:2048
	v_add_f32_e32 v194, v188, v189
	v_add_f32_e32 v198, v190, v191
	v_add_f32_e32 v202, v78, v79
	v_add_f32_e32 v206, v80, v81
	v_add_f32_e32 v210, v82, v83
	v_add_f32_e32 v214, v84, v85
	v_add_f32_e32 v218, v86, v87
	v_add_f32_e32 v222, v88, v89
	v_add_f32_dpp v194, v194, v194 quad_perm:[1,0,3,2] row_mask:0xf bank_mask:0xf bound_ctrl:1
	v_add_f32_dpp v198, v198, v198 quad_perm:[1,0,3,2] row_mask:0xf bank_mask:0xf bound_ctrl:1
	v_add_f32_dpp v202, v202, v202 quad_perm:[1,0,3,2] row_mask:0xf bank_mask:0xf bound_ctrl:1
	v_add_f32_dpp v206, v206, v206 quad_perm:[1,0,3,2] row_mask:0xf bank_mask:0xf bound_ctrl:1
	v_add_f32_dpp v210, v210, v210 quad_perm:[1,0,3,2] row_mask:0xf bank_mask:0xf bound_ctrl:1
; template <int CTRL> __device__ __forceinline__ float dpp_mov(float v) { return __builtin_bit_cast(float, __builtin_amdgcn_update_dpp(0, __builtin_bit_cast(int, v), CTRL, 0xf, 0xf, true)); }
; __device__ __forceinline__ float half_wave_sum(float v) {
;     v += dpp_mov<0xB1>(v);
;     v += dpp_mov<0x4E>(v);
;     v += dpp_mov<0x141>(v);
;     v += dpp_mov<0x140>(v);
;     v += __shfl_xor(v, 16);
;     return v;
; }
; __device__ __forceinline__ void gn_swish_store(float v0, float v1, f32x2v gg, f32x2v gb, unsigned* dst) {
;     const float mean = half_wave_sum(v0 + v1) * (1.0f / 64.0f); const float d0 = v0 - mean, d1 = v1 - mean;
;     const float rstd = rsqrtf(half_wave_sum(d0 * d0 + d1 * d1) * (1.0f / 64.0f) + LN_EPS);
	v_add_f32_dpp v214, v214, v214 quad_perm:[1,0,3,2] row_mask:0xf bank_mask:0xf bound_ctrl:1
	v_add_f32_dpp v218, v218, v218 quad_perm:[1,0,3,2] row_mask:0xf bank_mask:0xf bound_ctrl:1
	v_add_f32_dpp v222, v222, v222 quad_perm:[1,0,3,2] row_mask:0xf bank_mask:0xf bound_ctrl:1
	v_add_f32_dpp v194, v194, v194 quad_perm:[2,3,0,1] row_mask:0xf bank_mask:0xf bound_ctrl:1
	v_add_f32_dpp v198, v198, v198 quad_perm:[2,3,0,1] row_mask:0xf bank_mask:0xf bound_ctrl:1
	v_add_f32_dpp v202, v202, v202 quad_perm:[2,3,0,1] row_mask:0xf bank_mask:0xf bound_ctrl:1
	v_add_f32_dpp v206, v206, v206 quad_perm:[2,3,0,1] row_mask:0xf bank_mask:0xf bound_ctrl:1
	v_add_f32_dpp v210, v210, v210 quad_perm:[2,3,0,1] row_mask:0xf bank_mask:0xf bound_ctrl:1
	v_add_f32_dpp v214, v214, v214 quad_perm:[2,3,0,1] row_mask:0xf bank_mask:0xf bound_ctrl:1
	v_add_f32_dpp v218, v218, v218 quad_perm:[2,3,0,1] row_mask:0xf bank_mask:0xf bound_ctrl:1
	v_add_f32_dpp v222, v222, v222 quad_perm:[2,3,0,1] row_mask:0xf bank_mask:0xf bound_ctrl:1
	v_add_f32_dpp v194, v194, v194 row_half_mirror row_mask:0xf bank_mask:0xf bound_ctrl:1
	v_add_f32_dpp v198, v198, v198 row_half_mirror row_mask:0xf bank_mask:0xf bound_ctrl:1
	v_add_f32_dpp v202, v202, v202 row_half_mirror row_mask:0xf bank_mask:0xf bound_ctrl:1
	v_add_f32_dpp v206, v206, v206 row_half_mirror row_mask:0xf bank_mask:0xf bound_ctrl:1
	v_add_f32_dpp v210, v210, v210 row_half_mirror row_mask:0xf bank_mask:0xf bound_ctrl:1
	v_add_f32_dpp v214, v214, v214 row_half_mirror row_mask:0xf bank_mask:0xf bound_ctrl:1
	v_add_f32_dpp v218, v218, v218 row_half_mirror row_mask:0xf bank_mask:0xf bound_ctrl:1
	v_add_f32_dpp v222, v222, v222 row_half_mirror row_mask:0xf bank_mask:0xf bound_ctrl:1
	v_add_f32_dpp v194, v194, v194 row_mirror row_mask:0xf bank_mask:0xf bound_ctrl:1
	v_add_f32_dpp v198, v198, v198 row_mirror row_mask:0xf bank_mask:0xf bound_ctrl:1
	v_add_f32_dpp v202, v202, v202 row_mirror row_mask:0xf bank_mask:0xf bound_ctrl:1
	v_add_f32_dpp v206, v206, v206 row_mirror row_mask:0xf bank_mask:0xf bound_ctrl:1
	v_add_f32_dpp v210, v210, v210 row_mirror row_mask:0xf bank_mask:0xf bound_ctrl:1
	v_add_f32_dpp v214, v214, v214 row_mirror row_mask:0xf bank_mask:0xf bound_ctrl:1
	v_add_f32_dpp v218, v218, v218 row_mirror row_mask:0xf bank_mask:0xf bound_ctrl:1
	v_add_f32_dpp v222, v222, v222 row_mirror row_mask:0xf bank_mask:0xf bound_ctrl:1
	ds_bpermute_b32 v195, v239, v194
	ds_bpermute_b32 v199, v239, v198
	ds_bpermute_b32 v203, v239, v202
	ds_bpermute_b32 v207, v239, v206
	ds_bpermute_b32 v211, v239, v210
	ds_bpermute_b32 v215, v239, v214
	ds_bpermute_b32 v219, v239, v218
	ds_bpermute_b32 v223, v239, v222
	s_waitcnt lgkmcnt(7)
	v_add_f32_e32 v194, v194, v195
	s_waitcnt lgkmcnt(6)
	v_add_f32_e32 v198, v198, v199
	s_waitcnt lgkmcnt(5)
	v_add_f32_e32 v202, v202, v203
	s_waitcnt lgkmcnt(4)
	v_add_f32_e32 v206, v206, v207
	s_waitcnt lgkmcnt(3)
	v_add_f32_e32 v210, v210, v211
	s_waitcnt lgkmcnt(2)
	v_add_f32_e32 v214, v214, v215
	s_waitcnt lgkmcnt(1)
	v_add_f32_e32 v218, v218, v219
	s_waitcnt lgkmcnt(0)
	v_add_f32_e32 v222, v222, v223
	v_mul_f32_e32 v194, 0x3c800000, v194
	v_mul_f32_e32 v198, 0x3c800000, v198
	v_mul_f32_e32 v202, 0x3c800000, v202
	v_mul_f32_e32 v206, 0x3c800000, v206
	v_mul_f32_e32 v210, 0x3c800000, v210
	v_mul_f32_e32 v214, 0x3c800000, v214
	v_mul_f32_e32 v218, 0x3c800000, v218
	v_mul_f32_e32 v222, 0x3c800000, v222
	v_pk_add_f32 v[188:189], v[188:189], v[194:195] op_sel_hi:[1,0] neg_lo:[0,1] neg_hi:[0,1]
	v_pk_add_f32 v[190:191], v[190:191], v[198:199] op_sel_hi:[1,0] neg_lo:[0,1] neg_hi:[0,1]
	v_pk_add_f32 v[78:79], v[78:79], v[202:203] op_sel_hi:[1,0] neg_lo:[0,1] neg_hi:[0,1]
	v_pk_add_f32 v[80:81], v[80:81], v[206:207] op_sel_hi:[1,0] neg_lo:[0,1] neg_hi:[0,1]
	v_pk_add_f32 v[82:83], v[82:83], v[210:211] op_sel_hi:[1,0] neg_lo:[0,1] neg_hi:[0,1]
	v_pk_add_f32 v[84:85], v[84:85], v[214:215] op_sel_hi:[1,0] neg_lo:[0,1] neg_hi:[0,1]
	v_pk_add_f32 v[86:87], v[86:87], v[218:219] op_sel_hi:[1,0] neg_lo:[0,1] neg_hi:[0,1]
	v_pk_add_f32 v[88:89], v[88:89], v[222:223] op_sel_hi:[1,0] neg_lo:[0,1] neg_hi:[0,1]
	v_pk_mul_f32 v[196:197], v[188:189], v[188:189]
	v_pk_mul_f32 v[200:201], v[190:191], v[190:191]
	v_pk_mul_f32 v[204:205], v[78:79], v[78:79]
	v_pk_mul_f32 v[208:209], v[80:81], v[80:81]
	v_pk_mul_f32 v[212:213], v[82:83], v[82:83]
	v_pk_mul_f32 v[216:217], v[84:85], v[84:85]
	v_pk_mul_f32 v[220:221], v[86:87], v[86:87]
	v_pk_mul_f32 v[224:225], v[88:89], v[88:89]
	v_add_f32_e32 v194, v196, v197
	v_add_f32_e32 v198, v200, v201
	v_add_f32_e32 v202, v204, v205
	v_add_f32_e32 v206, v208, v209
	v_add_f32_e32 v210, v212, v213
	v_add_f32_e32 v214, v216, v217
	v_add_f32_e32 v218, v220, v221
	v_add_f32_e32 v222, v224, v225
	v_add_f32_dpp v194, v194, v194 quad_perm:[1,0,3,2] row_mask:0xf bank_mask:0xf bound_ctrl:1
	v_add_f32_dpp v198, v198, v198 quad_perm:[1,0,3,2] row_mask:0xf bank_mask:0xf bound_ctrl:1
	v_add_f32_dpp v202, v202, v202 quad_perm:[1,0,3,2] row_mask:0xf bank_mask:0xf bound_ctrl:1
	v_add_f32_dpp v206, v206, v206 quad_perm:[1,0,3,2] row_mask:0xf bank_mask:0xf bound_ctrl:1
	v_add_f32_dpp v210, v210, v210 quad_perm:[1,0,3,2] row_mask:0xf bank_mask:0xf bound_ctrl:1
	v_add_f32_dpp v214, v214, v214 quad_perm:[1,0,3,2] row_mask:0xf bank_mask:0xf bound_ctrl:1
	v_add_f32_dpp v218, v218, v218 quad_perm:[1,0,3,2] row_mask:0xf bank_mask:0xf bound_ctrl:1
	v_add_f32_dpp v222, v222, v222 quad_perm:[1,0,3,2] row_mask:0xf bank_mask:0xf bound_ctrl:1
	v_add_f32_dpp v194, v194, v194 quad_perm:[2,3,0,1] row_mask:0xf bank_mask:0xf bound_ctrl:1
	v_add_f32_dpp v198, v198, v198 quad_perm:[2,3,0,1] row_mask:0xf bank_mask:0xf bound_ctrl:1
; template <int CTRL> __device__ __forceinline__ float dpp_mov(float v) { return __builtin_bit_cast(float, __builtin_amdgcn_update_dpp(0, __builtin_bit_cast(int, v), CTRL, 0xf, 0xf, true)); }
; __device__ __forceinline__ float half_wave_sum(float v) {
;     v += dpp_mov<0xB1>(v);
;     v += dpp_mov<0x4E>(v);
;     v += dpp_mov<0x141>(v);
;     v += dpp_mov<0x140>(v);
;     v += __shfl_xor(v, 16);
;     return v;
; }
; __device__ __forceinline__ void gn_swish_store(float v0, float v1, f32x2v gg, f32x2v gb, unsigned* dst) {
;     const float mean = half_wave_sum(v0 + v1) * (1.0f / 64.0f); const float d0 = v0 - mean, d1 = v1 - mean;
	v_add_f32_dpp v202, v202, v202 quad_perm:[2,3,0,1] row_mask:0xf bank_mask:0xf bound_ctrl:1
	v_add_f32_dpp v206, v206, v206 quad_perm:[2,3,0,1] row_mask:0xf bank_mask:0xf bound_ctrl:1
	v_add_f32_dpp v210, v210, v210 quad_perm:[2,3,0,1] row_mask:0xf bank_mask:0xf bound_ctrl:1
	v_add_f32_dpp v214, v214, v214 quad_perm:[2,3,0,1] row_mask:0xf bank_mask:0xf bound_ctrl:1
	v_add_f32_dpp v218, v218, v218 quad_perm:[2,3,0,1] row_mask:0xf bank_mask:0xf bound_ctrl:1
	v_add_f32_dpp v222, v222, v222 quad_perm:[2,3,0,1] row_mask:0xf bank_mask:0xf bound_ctrl:1
	v_add_f32_dpp v194, v194, v194 row_half_mirror row_mask:0xf bank_mask:0xf bound_ctrl:1
	v_add_f32_dpp v198, v198, v198 row_half_mirror row_mask:0xf bank_mask:0xf bound_ctrl:1
	v_add_f32_dpp v202, v202, v202 row_half_mirror row_mask:0xf bank_mask:0xf bound_ctrl:1
	v_add_f32_dpp v206, v206, v206 row_half_mirror row_mask:0xf bank_mask:0xf bound_ctrl:1
	v_add_f32_dpp v210, v210, v210 row_half_mirror row_mask:0xf bank_mask:0xf bound_ctrl:1
	v_add_f32_dpp v214, v214, v214 row_half_mirror row_mask:0xf bank_mask:0xf bound_ctrl:1
	v_add_f32_dpp v218, v218, v218 row_half_mirror row_mask:0xf bank_mask:0xf bound_ctrl:1
	v_add_f32_dpp v222, v222, v222 row_half_mirror row_mask:0xf bank_mask:0xf bound_ctrl:1
	v_add_f32_dpp v194, v194, v194 row_mirror row_mask:0xf bank_mask:0xf bound_ctrl:1
	v_add_f32_dpp v198, v198, v198 row_mirror row_mask:0xf bank_mask:0xf bound_ctrl:1
	v_add_f32_dpp v202, v202, v202 row_mirror row_mask:0xf bank_mask:0xf bound_ctrl:1
	v_add_f32_dpp v206, v206, v206 row_mirror row_mask:0xf bank_mask:0xf bound_ctrl:1
	v_add_f32_dpp v210, v210, v210 row_mirror row_mask:0xf bank_mask:0xf bound_ctrl:1
	v_add_f32_dpp v214, v214, v214 row_mirror row_mask:0xf bank_mask:0xf bound_ctrl:1
	v_add_f32_dpp v218, v218, v218 row_mirror row_mask:0xf bank_mask:0xf bound_ctrl:1
	v_add_f32_dpp v222, v222, v222 row_mirror row_mask:0xf bank_mask:0xf bound_ctrl:1
	ds_bpermute_b32 v195, v239, v194
	ds_bpermute_b32 v199, v239, v198
	ds_bpermute_b32 v203, v239, v202
	ds_bpermute_b32 v207, v239, v206
	ds_bpermute_b32 v211, v239, v210
	ds_bpermute_b32 v215, v239, v214
	ds_bpermute_b32 v219, v239, v218
	ds_bpermute_b32 v223, v239, v222
	s_waitcnt lgkmcnt(7)
	v_add_f32_e32 v194, v194, v195
	s_waitcnt lgkmcnt(6)
	v_add_f32_e32 v198, v198, v199
	s_waitcnt lgkmcnt(5)
	v_add_f32_e32 v202, v202, v203
	s_waitcnt lgkmcnt(4)
	v_add_f32_e32 v206, v206, v207
	s_waitcnt lgkmcnt(3)
	v_add_f32_e32 v210, v210, v211
	s_waitcnt lgkmcnt(2)
	v_add_f32_e32 v214, v214, v215
	s_waitcnt lgkmcnt(1)
	v_add_f32_e32 v218, v218, v219
	s_waitcnt lgkmcnt(0)
; __device__ __forceinline__ unsigned pk2(float lo, float hi) { f32x2v v = {lo, hi}; b16x2v b = __builtin_convertvector(v, b16x2v); return __builtin_bit_cast(unsigned, b); }
; __device__ __forceinline__ float fsigmoid(float x) { return __builtin_amdgcn_rcpf(1.0f + __expf(-x)); }
; __device__ __forceinline__ void gn_swish_store(float v0, float v1, f32x2v gg, f32x2v gb, unsigned* dst) {
;     const float mean = half_wave_sum(v0 + v1) * (1.0f / 64.0f); const float d0 = v0 - mean, d1 = v1 - mean;
;     const float rstd = rsqrtf(half_wave_sum(d0 * d0 + d1 * d1) * (1.0f / 64.0f) + LN_EPS);
;     float y0 = d0 * rstd * gg.x + gb.x, y1 = d1 * rstd * gg.y + gb.y;
;     y0 = y0 * fsigmoid(y0); y1 = y1 * fsigmoid(y1);
;     *dst = pk2(y0, y1);
; }
; __device__ __forceinline__ void mixer_prompt_run(const Args& p, int run, int c2) {
;     ...
;             for (int t = 0; t < 8; ++t) gn_swish_store(a[t].x, a[t].y, gg, gb, M32 + (rowb + t0 + 8 * hh + t) * 512 + c2);
; __device__ __forceinline__ void p2_mixer(const Args& p, int G, int bid, int tid) {
;     ...
;     for (int it = vcu; it < 512 + 64; it += G) {
;         if (it < 512) mixer_prompt_run(p, 2 * it + half, c2);
	v_add_f32_e32 v222, v222, v223
	v_mul_f32_e32 v194, 0x3c800000, v194
	v_mul_f32_e32 v198, 0x3c800000, v198
	v_mul_f32_e32 v202, 0x3c800000, v202
	v_mul_f32_e32 v206, 0x3c800000, v206
	v_mul_f32_e32 v210, 0x3c800000, v210
	v_mul_f32_e32 v214, 0x3c800000, v214
	v_mul_f32_e32 v218, 0x3c800000, v218
	v_mul_f32_e32 v222, 0x3c800000, v222
	v_add_f32_e32 v194, 0x3727c5ac, v194
	v_add_f32_e32 v198, 0x3727c5ac, v198
	v_add_f32_e32 v202, 0x3727c5ac, v202
	v_add_f32_e32 v206, 0x3727c5ac, v206
	v_add_f32_e32 v210, 0x3727c5ac, v210
	v_add_f32_e32 v214, 0x3727c5ac, v214
	v_add_f32_e32 v218, 0x3727c5ac, v218
	v_add_f32_e32 v222, 0x3727c5ac, v222
	v_rsq_f32_e32 v194, v194
	v_rsq_f32_e32 v198, v198
	v_rsq_f32_e32 v202, v202
	v_rsq_f32_e32 v206, v206
	v_rsq_f32_e32 v210, v210
	v_rsq_f32_e32 v214, v214
	v_rsq_f32_e32 v218, v218
	v_rsq_f32_e32 v222, v222
	v_pk_mul_f32 v[188:189], v[188:189], v[194:195] op_sel_hi:[1,0]
	v_pk_mul_f32 v[190:191], v[190:191], v[198:199] op_sel_hi:[1,0]
	v_pk_mul_f32 v[78:79], v[78:79], v[202:203] op_sel_hi:[1,0]
	v_pk_mul_f32 v[80:81], v[80:81], v[206:207] op_sel_hi:[1,0]
	v_pk_mul_f32 v[82:83], v[82:83], v[210:211] op_sel_hi:[1,0]
	v_pk_mul_f32 v[84:85], v[84:85], v[214:215] op_sel_hi:[1,0]
	v_pk_mul_f32 v[86:87], v[86:87], v[218:219] op_sel_hi:[1,0]
	v_pk_mul_f32 v[88:89], v[88:89], v[222:223] op_sel_hi:[1,0]
	v_pk_fma_f32 v[188:189], v[188:189], v[92:93], v[94:95]
	v_pk_fma_f32 v[190:191], v[190:191], v[92:93], v[94:95]
	v_pk_fma_f32 v[78:79], v[78:79], v[92:93], v[94:95]
	v_pk_fma_f32 v[80:81], v[80:81], v[92:93], v[94:95]
	v_pk_fma_f32 v[82:83], v[82:83], v[92:93], v[94:95]
	v_pk_fma_f32 v[84:85], v[84:85], v[92:93], v[94:95]
	v_pk_fma_f32 v[86:87], v[86:87], v[92:93], v[94:95]
	v_pk_fma_f32 v[88:89], v[88:89], v[92:93], v[94:95]
	v_mul_f32_e32 v196, 0xbfb8aa3b, v188
	v_mul_f32_e32 v197, 0xbfb8aa3b, v189
	v_mul_f32_e32 v200, 0xbfb8aa3b, v190
	v_mul_f32_e32 v201, 0xbfb8aa3b, v191
	v_mul_f32_e32 v204, 0xbfb8aa3b, v78
	v_mul_f32_e32 v205, 0xbfb8aa3b, v79
	v_mul_f32_e32 v208, 0xbfb8aa3b, v80
	v_mul_f32_e32 v209, 0xbfb8aa3b, v81
	v_mul_f32_e32 v212, 0xbfb8aa3b, v82
	v_mul_f32_e32 v213, 0xbfb8aa3b, v83
	v_mul_f32_e32 v216, 0xbfb8aa3b, v84
	v_mul_f32_e32 v217, 0xbfb8aa3b, v85
	v_mul_f32_e32 v220, 0xbfb8aa3b, v86
	v_mul_f32_e32 v221, 0xbfb8aa3b, v87
	v_mul_f32_e32 v224, 0xbfb8aa3b, v88
	v_mul_f32_e32 v225, 0xbfb8aa3b, v89
	v_exp_f32_e32 v196, v196
	v_exp_f32_e32 v197, v197
	v_exp_f32_e32 v200, v200
	v_exp_f32_e32 v201, v201
	v_exp_f32_e32 v204, v204
	v_exp_f32_e32 v205, v205
	v_exp_f32_e32 v208, v208
	v_exp_f32_e32 v209, v209
	v_exp_f32_e32 v212, v212
	v_exp_f32_e32 v213, v213
	v_exp_f32_e32 v216, v216
	v_exp_f32_e32 v217, v217
	v_exp_f32_e32 v220, v220
	v_exp_f32_e32 v221, v221
	v_exp_f32_e32 v224, v224
	v_exp_f32_e32 v225, v225
	v_add_f32_e32 v196, 1.0, v196
	v_add_f32_e32 v197, 1.0, v197
	v_add_f32_e32 v200, 1.0, v200
	v_add_f32_e32 v201, 1.0, v201
	v_add_f32_e32 v204, 1.0, v204
	v_add_f32_e32 v205, 1.0, v205
	v_add_f32_e32 v208, 1.0, v208
	v_add_f32_e32 v209, 1.0, v209
	v_add_f32_e32 v212, 1.0, v212
	v_add_f32_e32 v213, 1.0, v213
	v_add_f32_e32 v216, 1.0, v216
	v_add_f32_e32 v217, 1.0, v217
	v_add_f32_e32 v220, 1.0, v220
	v_add_f32_e32 v221, 1.0, v221
	v_add_f32_e32 v224, 1.0, v224
	v_add_f32_e32 v225, 1.0, v225
	v_rcp_f32_e32 v196, v196
	v_rcp_f32_e32 v197, v197
	v_rcp_f32_e32 v200, v200
	v_rcp_f32_e32 v201, v201
	v_rcp_f32_e32 v204, v204
	v_rcp_f32_e32 v205, v205
	v_rcp_f32_e32 v208, v208
	v_rcp_f32_e32 v209, v209
	v_rcp_f32_e32 v212, v212
	v_rcp_f32_e32 v213, v213
	v_rcp_f32_e32 v216, v216
	v_rcp_f32_e32 v217, v217
	v_rcp_f32_e32 v220, v220
	v_rcp_f32_e32 v221, v221
	v_rcp_f32_e32 v224, v224
	v_rcp_f32_e32 v225, v225
	v_pk_mul_f32 v[188:189], v[188:189], v[196:197]
	v_pk_mul_f32 v[190:191], v[190:191], v[200:201]
	v_pk_mul_f32 v[78:79], v[78:79], v[204:205]
	v_pk_mul_f32 v[80:81], v[80:81], v[208:209]
	v_pk_mul_f32 v[82:83], v[82:83], v[212:213]
	v_pk_mul_f32 v[84:85], v[84:85], v[216:217]
	v_pk_mul_f32 v[86:87], v[86:87], v[220:221]
	v_pk_mul_f32 v[88:89], v[88:89], v[224:225]
	v_cvt_pk_bf16_f32 v194, v188, v189
	v_cvt_pk_bf16_f32 v198, v190, v191
	v_cvt_pk_bf16_f32 v202, v78, v79
	v_cvt_pk_bf16_f32 v206, v80, v81
	v_cvt_pk_bf16_f32 v210, v82, v83
	v_cvt_pk_bf16_f32 v214, v84, v85
	v_cvt_pk_bf16_f32 v218, v86, v87
	v_cvt_pk_bf16_f32 v222, v88, v89
	s_add_u32 s70, s70, 0x2000
	s_addc_u32 s71, s71, 0
	global_store_dword v105, v194, s[70:71] offset:-4096
	global_store_dword v105, v198, s[70:71] offset:-2048
	global_store_dword v105, v202, s[70:71] offset:0
	global_store_dword v105, v206, s[70:71] offset:2048
	s_add_u32 s70, s70, 0x2000
	s_addc_u32 s71, s71, 0
	global_store_dword v105, v210, s[70:71] offset:-4096
	global_store_dword v105, v214, s[70:71] offset:-2048
	global_store_dword v105, v218, s[70:71] offset:0
	global_store_dword v105, v222, s[70:71] offset:2048
	s_branch .Lmx_done
